# P0 SSM coefficient prep: 31 serialized C-matrix loads issued together
# speedup vs baseline: 1.0136x; 1.0020x over previous
.LBB0_48:
	v_lshl_add_u64 v[12:13], s[56:57], 0, v[8:9]
	global_load_dword v7, v[12:13], off
	v_lshl_add_u64 v[14:15], s[58:59], 0, v[8:9]
	v_bfe_u32 v24, v0, 6, 6
	v_ashrrev_i32_e32 v25, 12, v0
	s_mov_b32 s96, 0x3fb8aa3b
	s_mov_b32 s12, 0xeb1c432d
	s_mov_b32 s13, 0xbf1a36e2
	v_lshl_add_u64 v[52:53], s[64:65], 0, v[10:11]
	s_add_u32 s64, s64, s46
	s_addc_u32 s65, s65, s47
	s_waitcnt vmcnt(0)
	v_cvt_f64_f32_e32 v[12:13], v7
	global_load_dword v7, v[14:15], off
	v_lshl_or_b32 v14, v25, 6, v24
	v_ashrrev_i32_e32 v15, 31, v14
	v_lshl_add_u64 v[16:17], v[14:15], 2, s[60:61]
	v_min_f64 v[12:13], v[12:13], s[12:13]
	s_mov_b32 s12, 0
	s_mov_b32 s13, 0x40080000
	v_lshl_add_u32 v24, v24, 1, v25
	v_ashrrev_i32_e32 v25, 31, v24
	v_lshlrev_b64 v[56:57], 12, v[24:25]
	v_lshl_add_u64 v[58:59], v[2:3], 0, v[56:57]
	s_waitcnt vmcnt(0)
	v_cvt_f64_f32_e32 v[18:19], v7
	global_load_dword v7, v[16:17], off
	s_waitcnt vmcnt(0)
	v_mul_f32_e32 v16, 0x3fb8aa3b, v7
	v_fma_f32 v17, v7, s96, -v16
	v_rndne_f32_e32 v20, v16
	v_fmac_f32_e32 v17, 0x32a5705f, v7
	v_sub_f32_e32 v16, v16, v20
	v_add_f32_e32 v16, v16, v17
	v_exp_f32_e32 v16, v16
	v_cvt_i32_f32_e32 v17, v20
	s_mov_b32 s96, 0xc2ce8ed0
	v_cmp_ngt_f32_e32 vcc, s96, v7
	s_mov_b32 s96, 0x42b17218
	v_ldexp_f32 v16, v16, v17
	v_cndmask_b32_e32 v16, 0, v16, vcc
	v_cmp_nlt_f32_e32 vcc, s96, v7
	s_mov_b32 s96, s94
	s_nop 0
	v_cndmask_b32_e32 v7, v1, v16, vcc
	v_cvt_f64_f32_e32 v[16:17], v7
	v_mul_f64 v[20:21], v[12:13], v[16:17]
	v_mul_f64 v[28:29], v[20:21], v[20:21]
	v_fma_f64 v[26:27], v[12:13], v[16:17], 1.0
	v_mul_f64 v[30:31], v[28:29], 0.5
	v_fmac_f64_e32 v[26:27], 0.5, v[28:29]
	v_mul_f64 v[28:29], v[20:21], v[30:31]
	v_div_scale_f64 v[30:31], vcc, s[12:13], s[12:13], v[28:29]
	v_rcp_f64_e32 v[32:33], v[30:31]
	v_ashrrev_i32_e32 v7, 31, v6
	v_fma_f64 v[34:35], -v[30:31], v[32:33], 1.0
	v_fmac_f64_e32 v[32:33], v[32:33], v[34:35]
	v_fma_f64 v[34:35], -v[30:31], v[32:33], 1.0
	v_fmac_f64_e32 v[32:33], v[32:33], v[34:35]
	v_div_scale_f64 v[34:35], vcc, v[28:29], s[12:13], v[28:29]
	v_mul_f64 v[36:37], v[34:35], v[32:33]
	v_fma_f64 v[30:31], -v[30:31], v[36:37], v[34:35]
	s_nop 1
	v_div_fmas_f64 v[30:31], v[30:31], v[32:33], v[36:37]
	v_div_fixup_f64 v[28:29], v[30:31], s[12:13], v[28:29]
	v_add_f64 v[26:27], v[26:27], v[28:29]
	v_mul_f64 v[28:29], v[20:21], v[28:29]
	v_ldexp_f64 v[30:31], v[28:29], -2
	s_mov_b32 s12, 0
	v_fmac_f64_e32 v[26:27], 0x3fd00000, v[28:29]
	v_mul_f64 v[28:29], v[20:21], v[30:31]
	s_mov_b32 s13, 0x40140000
	v_div_scale_f64 v[30:31], vcc, s[12:13], s[12:13], v[28:29]
	v_rcp_f64_e32 v[32:33], v[30:31]
	s_nop 0
	v_fma_f64 v[34:35], -v[30:31], v[32:33], 1.0
	v_fmac_f64_e32 v[32:33], v[32:33], v[34:35]
	v_fma_f64 v[34:35], -v[30:31], v[32:33], 1.0
	v_fmac_f64_e32 v[32:33], v[32:33], v[34:35]
	v_div_scale_f64 v[34:35], vcc, v[28:29], s[12:13], v[28:29]
	v_mul_f64 v[36:37], v[34:35], v[32:33]
	v_fma_f64 v[30:31], -v[30:31], v[36:37], v[34:35]
	s_nop 1
	v_div_fmas_f64 v[30:31], v[30:31], v[32:33], v[36:37]
	v_div_fixup_f64 v[28:29], v[30:31], s[12:13], v[28:29]
	v_add_f64 v[26:27], v[26:27], v[28:29]
	v_mul_f64 v[28:29], v[20:21], v[28:29]
	v_div_scale_f64 v[30:31], vcc, s[78:79], s[78:79], v[28:29]
	v_rcp_f64_e32 v[32:33], v[30:31]
	s_mov_b32 s12, 0
	s_mov_b32 s13, 0x401c0000
	v_fma_f64 v[34:35], -v[30:31], v[32:33], 1.0
	v_fmac_f64_e32 v[32:33], v[32:33], v[34:35]
	v_fma_f64 v[34:35], -v[30:31], v[32:33], 1.0
	v_fmac_f64_e32 v[32:33], v[32:33], v[34:35]
	v_div_scale_f64 v[34:35], vcc, v[28:29], s[78:79], v[28:29]
	v_mul_f64 v[36:37], v[34:35], v[32:33]
	v_fma_f64 v[30:31], -v[30:31], v[36:37], v[34:35]
	s_nop 1
	v_div_fmas_f64 v[30:31], v[30:31], v[32:33], v[36:37]
	v_div_fixup_f64 v[28:29], v[30:31], s[78:79], v[28:29]
	v_add_f64 v[26:27], v[26:27], v[28:29]
	v_mul_f64 v[28:29], v[20:21], v[28:29]
	v_div_scale_f64 v[30:31], vcc, s[12:13], s[12:13], v[28:29]
	v_rcp_f64_e32 v[32:33], v[30:31]
	s_nop 0
	v_fma_f64 v[34:35], -v[30:31], v[32:33], 1.0
	v_fmac_f64_e32 v[32:33], v[32:33], v[34:35]
	v_fma_f64 v[34:35], -v[30:31], v[32:33], 1.0
	v_fmac_f64_e32 v[32:33], v[32:33], v[34:35]
	v_div_scale_f64 v[34:35], vcc, v[28:29], s[12:13], v[28:29]
	v_mul_f64 v[36:37], v[34:35], v[32:33]
	v_fma_f64 v[30:31], -v[30:31], v[36:37], v[34:35]
	s_nop 1
	v_div_fmas_f64 v[30:31], v[30:31], v[32:33], v[36:37]
	v_div_fixup_f64 v[28:29], v[30:31], s[12:13], v[28:29]
	v_add_f64 v[26:27], v[26:27], v[28:29]
	v_mul_f64 v[28:29], v[20:21], v[28:29]
	v_ldexp_f64 v[30:31], v[28:29], -3
	s_mov_b32 s12, 0
	v_fmac_f64_e32 v[26:27], 0x3fc00000, v[28:29]
	v_mul_f64 v[28:29], v[20:21], v[30:31]
	s_mov_b32 s13, 0x40220000
	v_div_scale_f64 v[30:31], vcc, s[12:13], s[12:13], v[28:29]
	v_rcp_f64_e32 v[32:33], v[30:31]
	s_nop 0
	v_fma_f64 v[34:35], -v[30:31], v[32:33], 1.0
	v_fmac_f64_e32 v[32:33], v[32:33], v[34:35]
	v_fma_f64 v[34:35], -v[30:31], v[32:33], 1.0
	v_fmac_f64_e32 v[32:33], v[32:33], v[34:35]
	v_div_scale_f64 v[34:35], vcc, v[28:29], s[12:13], v[28:29]
	v_mul_f64 v[36:37], v[34:35], v[32:33]
	v_fma_f64 v[30:31], -v[30:31], v[36:37], v[34:35]
	s_nop 1
	v_div_fmas_f64 v[30:31], v[30:31], v[32:33], v[36:37]
	v_div_fixup_f64 v[28:29], v[30:31], s[12:13], v[28:29]
	s_mov_b32 s12, 0
	v_add_f64 v[26:27], v[26:27], v[28:29]
	v_mul_f64 v[28:29], v[20:21], v[28:29]
	s_mov_b32 s13, 0x40240000
	v_div_scale_f64 v[30:31], vcc, s[12:13], s[12:13], v[28:29]
	v_rcp_f64_e32 v[32:33], v[30:31]
	s_nop 0
	v_fma_f64 v[34:35], -v[30:31], v[32:33], 1.0
	v_fmac_f64_e32 v[32:33], v[32:33], v[34:35]
	v_fma_f64 v[34:35], -v[30:31], v[32:33], 1.0
	v_fmac_f64_e32 v[32:33], v[32:33], v[34:35]
	v_div_scale_f64 v[34:35], vcc, v[28:29], s[12:13], v[28:29]
	v_mul_f64 v[36:37], v[34:35], v[32:33]
	v_fma_f64 v[30:31], -v[30:31], v[36:37], v[34:35]
	s_nop 1
	v_div_fmas_f64 v[30:31], v[30:31], v[32:33], v[36:37]
	v_div_fixup_f64 v[28:29], v[30:31], s[12:13], v[28:29]
	s_mov_b32 s12, 0
	v_add_f64 v[26:27], v[26:27], v[28:29]
	v_mul_f64 v[28:29], v[20:21], v[28:29]
	s_mov_b32 s13, 0x40260000
	v_div_scale_f64 v[30:31], vcc, s[12:13], s[12:13], v[28:29]
	v_rcp_f64_e32 v[32:33], v[30:31]
	s_nop 0
	v_fma_f64 v[34:35], -v[30:31], v[32:33], 1.0
	v_fmac_f64_e32 v[32:33], v[32:33], v[34:35]
	v_fma_f64 v[34:35], -v[30:31], v[32:33], 1.0
	v_fmac_f64_e32 v[32:33], v[32:33], v[34:35]
	v_div_scale_f64 v[34:35], vcc, v[28:29], s[12:13], v[28:29]
	v_mul_f64 v[36:37], v[34:35], v[32:33]
	v_fma_f64 v[30:31], -v[30:31], v[36:37], v[34:35]
	s_nop 1
	v_div_fmas_f64 v[30:31], v[30:31], v[32:33], v[36:37]
	v_div_fixup_f64 v[28:29], v[30:31], s[12:13], v[28:29]
	v_add_f64 v[26:27], v[26:27], v[28:29]
	v_mul_f64 v[28:29], v[20:21], v[28:29]
	v_div_scale_f64 v[30:31], vcc, s[88:89], s[88:89], v[28:29]
	v_rcp_f64_e32 v[32:33], v[30:31]
	s_mov_b32 s12, 0
	s_mov_b32 s13, 0x402a0000
	v_fma_f64 v[34:35], -v[30:31], v[32:33], 1.0
	v_fmac_f64_e32 v[32:33], v[32:33], v[34:35]
	v_fma_f64 v[34:35], -v[30:31], v[32:33], 1.0
	v_fmac_f64_e32 v[32:33], v[32:33], v[34:35]
	v_div_scale_f64 v[34:35], vcc, v[28:29], s[88:89], v[28:29]
	v_mul_f64 v[36:37], v[34:35], v[32:33]
	v_fma_f64 v[30:31], -v[30:31], v[36:37], v[34:35]
	s_nop 1
	v_div_fmas_f64 v[30:31], v[30:31], v[32:33], v[36:37]
	v_div_fixup_f64 v[28:29], v[30:31], s[88:89], v[28:29]
	v_add_f64 v[26:27], v[26:27], v[28:29]
	v_mul_f64 v[28:29], v[20:21], v[28:29]
	v_div_scale_f64 v[30:31], vcc, s[12:13], s[12:13], v[28:29]
	v_rcp_f64_e32 v[32:33], v[30:31]
	s_nop 0
	v_fma_f64 v[34:35], -v[30:31], v[32:33], 1.0
	v_fmac_f64_e32 v[32:33], v[32:33], v[34:35]
	v_fma_f64 v[34:35], -v[30:31], v[32:33], 1.0
	v_fmac_f64_e32 v[32:33], v[32:33], v[34:35]
	v_div_scale_f64 v[34:35], vcc, v[28:29], s[12:13], v[28:29]
	v_mul_f64 v[36:37], v[34:35], v[32:33]
	v_fma_f64 v[30:31], -v[30:31], v[36:37], v[34:35]
	s_nop 1
	v_div_fmas_f64 v[30:31], v[30:31], v[32:33], v[36:37]
	v_div_fixup_f64 v[28:29], v[30:31], s[12:13], v[28:29]
	s_mov_b32 s12, 0
	v_mul_f64 v[20:21], v[20:21], v[28:29]
	s_mov_b32 s13, 0x402c0000
	v_add_f64 v[26:27], v[26:27], v[28:29]
	v_div_scale_f64 v[28:29], vcc, s[12:13], s[12:13], v[20:21]
	v_rcp_f64_e32 v[30:31], v[28:29]
	s_nop 0
	v_fma_f64 v[32:33], -v[28:29], v[30:31], 1.0
	v_fmac_f64_e32 v[30:31], v[30:31], v[32:33]
	v_fma_f64 v[32:33], -v[28:29], v[30:31], 1.0
	v_fmac_f64_e32 v[30:31], v[30:31], v[32:33]
	v_div_scale_f64 v[32:33], vcc, v[20:21], s[12:13], v[20:21]
	v_mul_f64 v[34:35], v[32:33], v[30:31]
	v_fma_f64 v[28:29], -v[28:29], v[34:35], v[32:33]
	s_nop 1
	v_div_fmas_f64 v[28:29], v[28:29], v[30:31], v[34:35]
	v_div_fixup_f64 v[20:21], v[28:29], s[12:13], v[20:21]
	v_add_f64 v[20:21], v[26:27], v[20:21]
	v_mul_f64 v[26:27], v[18:19], v[16:17]
	v_div_scale_f64 v[16:17], vcc, s[94:95], s[94:95], v[26:27]
	v_rcp_f64_e32 v[28:29], v[16:17]
	s_mov_b32 s12, 0
	s_mov_b32 s13, 0xc0340000
	v_fma_f64 v[30:31], -v[16:17], v[28:29], 1.0
	v_fmac_f64_e32 v[28:29], v[28:29], v[30:31]
	v_fma_f64 v[30:31], -v[16:17], v[28:29], 1.0
	v_fmac_f64_e32 v[28:29], v[28:29], v[30:31]
	v_div_scale_f64 v[30:31], vcc, v[26:27], s[94:95], v[26:27]
	v_mul_f64 v[32:33], v[30:31], v[28:29]
	v_fma_f64 v[16:17], -v[16:17], v[32:33], v[30:31]
	s_nop 1
	v_div_fmas_f64 v[16:17], v[16:17], v[28:29], v[32:33]
	v_div_fixup_f64 v[16:17], v[16:17], s[94:95], v[26:27]
	v_rndne_f64_e32 v[16:17], v[16:17]
	v_fmac_f64_e32 v[26:27], s[96:97], v[16:17]
	v_mul_f64 v[16:17], v[26:27], v[26:27]
	v_mul_f64 v[32:33], v[16:17], -v[26:27]
	v_div_scale_f64 v[34:35], vcc, s[78:79], s[78:79], v[32:33]
	v_rcp_f64_e32 v[36:37], v[34:35]
	v_mul_f64 v[28:29], v[16:17], 0.5
	v_mul_f64 v[28:29], v[16:17], v[28:29]
	v_fma_f64 v[30:31], v[16:17], -0.5, 1.0
	v_fma_f64 v[38:39], -v[34:35], v[36:37], 1.0
	v_fmac_f64_e32 v[36:37], v[36:37], v[38:39]
	v_fma_f64 v[38:39], -v[34:35], v[36:37], 1.0
	v_fmac_f64_e32 v[36:37], v[36:37], v[38:39]
	v_div_scale_f64 v[38:39], vcc, v[32:33], s[78:79], v[32:33]
	v_mul_f64 v[40:41], v[38:39], v[36:37]
	v_fma_f64 v[34:35], -v[34:35], v[40:41], v[38:39]
	s_movk_i32 s96, 0x1fff
	s_nop 0
	v_div_fmas_f64 v[34:35], v[34:35], v[36:37], v[40:41]
	v_div_fixup_f64 v[32:33], v[34:35], s[78:79], v[32:33]
	v_div_scale_f64 v[34:35], vcc, s[88:89], s[88:89], v[28:29]
	v_rcp_f64_e32 v[36:37], v[34:35]
	v_add_f64 v[26:27], v[26:27], v[32:33]
	v_mul_f64 v[32:33], v[16:17], v[32:33]
	v_fma_f64 v[38:39], -v[34:35], v[36:37], 1.0
	v_fmac_f64_e32 v[36:37], v[36:37], v[38:39]
	v_fma_f64 v[38:39], -v[34:35], v[36:37], 1.0
	v_fmac_f64_e32 v[36:37], v[36:37], v[38:39]
	v_div_scale_f64 v[38:39], vcc, v[28:29], s[88:89], v[28:29]
	v_mul_f64 v[40:41], v[38:39], v[36:37]
	v_fma_f64 v[34:35], -v[34:35], v[40:41], v[38:39]
	s_nop 1
	v_div_fmas_f64 v[34:35], v[34:35], v[36:37], v[40:41]
	v_div_fixup_f64 v[28:29], v[34:35], s[88:89], v[28:29]
	v_div_scale_f64 v[34:35], vcc, s[12:13], s[12:13], v[32:33]
	v_rcp_f64_e32 v[36:37], v[34:35]
	v_add_f64 v[30:31], v[30:31], v[28:29]
	v_mul_f64 v[28:29], v[16:17], v[28:29]
	v_fma_f64 v[38:39], -v[34:35], v[36:37], 1.0
	v_fmac_f64_e32 v[36:37], v[36:37], v[38:39]
	v_fma_f64 v[38:39], -v[34:35], v[36:37], 1.0
	v_fmac_f64_e32 v[36:37], v[36:37], v[38:39]
	v_div_scale_f64 v[38:39], vcc, v[32:33], s[12:13], v[32:33]
	v_mul_f64 v[40:41], v[38:39], v[36:37]
	v_fma_f64 v[34:35], -v[34:35], v[40:41], v[38:39]
	s_nop 1
	v_div_fmas_f64 v[34:35], v[34:35], v[36:37], v[40:41]
	v_div_fixup_f64 v[32:33], v[34:35], s[12:13], v[32:33]
	s_mov_b32 s12, 0
	s_mov_b32 s13, 0xc03e0000
	v_div_scale_f64 v[34:35], vcc, s[12:13], s[12:13], v[28:29]
	v_rcp_f64_e32 v[36:37], v[34:35]
	v_add_f64 v[26:27], v[26:27], v[32:33]
	v_mul_f64 v[32:33], v[16:17], v[32:33]
	v_fma_f64 v[38:39], -v[34:35], v[36:37], 1.0
	v_fmac_f64_e32 v[36:37], v[36:37], v[38:39]
	v_fma_f64 v[38:39], -v[34:35], v[36:37], 1.0
	v_fmac_f64_e32 v[36:37], v[36:37], v[38:39]
	v_div_scale_f64 v[38:39], vcc, v[28:29], s[12:13], v[28:29]
	v_mul_f64 v[40:41], v[38:39], v[36:37]
	v_fma_f64 v[34:35], -v[34:35], v[40:41], v[38:39]
	s_nop 1
	v_div_fmas_f64 v[34:35], v[34:35], v[36:37], v[40:41]
	v_div_fixup_f64 v[28:29], v[34:35], s[12:13], v[28:29]
	s_mov_b32 s12, 0
	s_mov_b32 s13, 0xc0450000
	v_div_scale_f64 v[34:35], vcc, s[12:13], s[12:13], v[32:33]
	v_rcp_f64_e32 v[36:37], v[34:35]
	v_add_f64 v[30:31], v[30:31], v[28:29]
	v_mul_f64 v[28:29], v[16:17], v[28:29]
	v_fma_f64 v[38:39], -v[34:35], v[36:37], 1.0
	v_fmac_f64_e32 v[36:37], v[36:37], v[38:39]
	v_fma_f64 v[38:39], -v[34:35], v[36:37], 1.0
	v_fmac_f64_e32 v[36:37], v[36:37], v[38:39]
	v_div_scale_f64 v[38:39], vcc, v[32:33], s[12:13], v[32:33]
	v_mul_f64 v[40:41], v[38:39], v[36:37]
	v_fma_f64 v[34:35], -v[34:35], v[40:41], v[38:39]
	s_nop 1
	v_div_fmas_f64 v[34:35], v[34:35], v[36:37], v[40:41]
	v_div_fixup_f64 v[32:33], v[34:35], s[12:13], v[32:33]
	s_mov_b32 s12, 0
	s_mov_b32 s13, 0xc04c0000
	v_div_scale_f64 v[34:35], vcc, s[12:13], s[12:13], v[28:29]
	v_rcp_f64_e32 v[36:37], v[34:35]
	v_add_f64 v[26:27], v[26:27], v[32:33]
	v_mul_f64 v[32:33], v[16:17], v[32:33]
	v_fma_f64 v[38:39], -v[34:35], v[36:37], 1.0
	v_fmac_f64_e32 v[36:37], v[36:37], v[38:39]
	v_fma_f64 v[38:39], -v[34:35], v[36:37], 1.0
	v_fmac_f64_e32 v[36:37], v[36:37], v[38:39]
	v_div_scale_f64 v[38:39], vcc, v[28:29], s[12:13], v[28:29]
	v_mul_f64 v[40:41], v[38:39], v[36:37]
	v_fma_f64 v[34:35], -v[34:35], v[40:41], v[38:39]
	s_nop 1
	v_div_fmas_f64 v[34:35], v[34:35], v[36:37], v[40:41]
	v_div_fixup_f64 v[28:29], v[34:35], s[12:13], v[28:29]
	s_mov_b32 s12, 0
	s_mov_b32 s13, 0xc0520000
	v_div_scale_f64 v[34:35], vcc, s[12:13], s[12:13], v[32:33]
	v_rcp_f64_e32 v[36:37], v[34:35]
	v_add_f64 v[30:31], v[30:31], v[28:29]
	v_mul_f64 v[28:29], v[16:17], v[28:29]
	v_fma_f64 v[38:39], -v[34:35], v[36:37], 1.0
	v_fmac_f64_e32 v[36:37], v[36:37], v[38:39]
	v_fma_f64 v[38:39], -v[34:35], v[36:37], 1.0
	v_fmac_f64_e32 v[36:37], v[36:37], v[38:39]
	v_div_scale_f64 v[38:39], vcc, v[32:33], s[12:13], v[32:33]
	v_mul_f64 v[40:41], v[38:39], v[36:37]
	v_fma_f64 v[34:35], -v[34:35], v[40:41], v[38:39]
	s_nop 1
	v_div_fmas_f64 v[34:35], v[34:35], v[36:37], v[40:41]
	v_div_fixup_f64 v[32:33], v[34:35], s[12:13], v[32:33]
	s_mov_b32 s12, 0
	s_mov_b32 s13, 0xc0568000
	v_div_scale_f64 v[34:35], vcc, s[12:13], s[12:13], v[28:29]
	v_rcp_f64_e32 v[36:37], v[34:35]
	v_add_f64 v[26:27], v[26:27], v[32:33]
	v_mul_f64 v[32:33], v[16:17], v[32:33]
	v_fma_f64 v[38:39], -v[34:35], v[36:37], 1.0
	v_fmac_f64_e32 v[36:37], v[36:37], v[38:39]
	v_fma_f64 v[38:39], -v[34:35], v[36:37], 1.0
	v_fmac_f64_e32 v[36:37], v[36:37], v[38:39]
	v_div_scale_f64 v[38:39], vcc, v[28:29], s[12:13], v[28:29]
	v_mul_f64 v[40:41], v[38:39], v[36:37]
	v_fma_f64 v[34:35], -v[34:35], v[40:41], v[38:39]
	s_nop 1
	v_div_fmas_f64 v[34:35], v[34:35], v[36:37], v[40:41]
	v_div_fixup_f64 v[28:29], v[34:35], s[12:13], v[28:29]
	v_div_scale_f64 v[34:35], vcc, s[0:1], s[0:1], v[32:33]
	v_rcp_f64_e32 v[36:37], v[34:35]
	v_add_f64 v[30:31], v[30:31], v[28:29]
	v_mul_f64 v[28:29], v[16:17], v[28:29]
	s_mov_b32 s12, 0
	v_fma_f64 v[38:39], -v[34:35], v[36:37], 1.0
	v_fmac_f64_e32 v[36:37], v[36:37], v[38:39]
	v_fma_f64 v[38:39], -v[34:35], v[36:37], 1.0
	v_fmac_f64_e32 v[36:37], v[36:37], v[38:39]
	v_div_scale_f64 v[38:39], vcc, v[32:33], s[0:1], v[32:33]
	v_mul_f64 v[40:41], v[38:39], v[36:37]
	v_fma_f64 v[34:35], -v[34:35], v[40:41], v[38:39]
	s_mov_b32 s13, 0xc06e0000
	s_nop 0
	v_div_fmas_f64 v[34:35], v[34:35], v[36:37], v[40:41]
	v_div_fixup_f64 v[32:33], v[34:35], s[0:1], v[32:33]
	v_div_scale_f64 v[34:35], vcc, s[10:11], s[10:11], v[28:29]
	v_rcp_f64_e32 v[36:37], v[34:35]
	v_add_f64 v[26:27], v[26:27], v[32:33]
	v_mul_f64 v[32:33], v[16:17], v[32:33]
	v_fma_f64 v[38:39], -v[34:35], v[36:37], 1.0
	v_fmac_f64_e32 v[36:37], v[36:37], v[38:39]
	v_fma_f64 v[38:39], -v[34:35], v[36:37], 1.0
	v_fmac_f64_e32 v[36:37], v[36:37], v[38:39]
	v_div_scale_f64 v[38:39], vcc, v[28:29], s[10:11], v[28:29]
	v_mul_f64 v[40:41], v[38:39], v[36:37]
	v_fma_f64 v[34:35], -v[34:35], v[40:41], v[38:39]
	s_nop 1
	v_div_fmas_f64 v[34:35], v[34:35], v[36:37], v[40:41]
	v_div_fixup_f64 v[28:29], v[34:35], s[10:11], v[28:29]
	v_div_scale_f64 v[34:35], vcc, s[6:7], s[6:7], v[32:33]
	v_rcp_f64_e32 v[36:37], v[34:35]
	v_add_f64 v[30:31], v[30:31], v[28:29]
	v_mul_f64 v[28:29], v[16:17], v[28:29]
	v_fma_f64 v[38:39], -v[34:35], v[36:37], 1.0
	v_fmac_f64_e32 v[36:37], v[36:37], v[38:39]
	v_fma_f64 v[38:39], -v[34:35], v[36:37], 1.0
	v_fmac_f64_e32 v[36:37], v[36:37], v[38:39]
	v_div_scale_f64 v[38:39], vcc, v[32:33], s[6:7], v[32:33]
	v_mul_f64 v[40:41], v[38:39], v[36:37]
	v_fma_f64 v[34:35], -v[34:35], v[40:41], v[38:39]
	s_nop 1
	v_div_fmas_f64 v[34:35], v[34:35], v[36:37], v[40:41]
	v_div_fixup_f64 v[32:33], v[34:35], s[6:7], v[32:33]
	v_div_scale_f64 v[34:35], vcc, s[68:69], s[68:69], v[28:29]
	v_rcp_f64_e32 v[36:37], v[34:35]
	v_add_f64 v[26:27], v[26:27], v[32:33]
	v_mul_f64 v[32:33], v[16:17], v[32:33]
	v_fma_f64 v[38:39], -v[34:35], v[36:37], 1.0
	v_fmac_f64_e32 v[36:37], v[36:37], v[38:39]
	v_fma_f64 v[38:39], -v[34:35], v[36:37], 1.0
	v_fmac_f64_e32 v[36:37], v[36:37], v[38:39]
	v_div_scale_f64 v[38:39], vcc, v[28:29], s[68:69], v[28:29]
	v_mul_f64 v[40:41], v[38:39], v[36:37]
	v_fma_f64 v[34:35], -v[34:35], v[40:41], v[38:39]
	s_nop 1
	v_div_fmas_f64 v[34:35], v[34:35], v[36:37], v[40:41]
	v_div_fixup_f64 v[28:29], v[34:35], s[68:69], v[28:29]
	v_div_scale_f64 v[34:35], vcc, s[72:73], s[72:73], v[32:33]
	v_rcp_f64_e32 v[36:37], v[34:35]
	v_add_f64 v[30:31], v[30:31], v[28:29]
	v_mul_f64 v[28:29], v[16:17], v[28:29]
	v_fma_f64 v[38:39], -v[34:35], v[36:37], 1.0
	v_fmac_f64_e32 v[36:37], v[36:37], v[38:39]
	v_fma_f64 v[38:39], -v[34:35], v[36:37], 1.0
	v_fmac_f64_e32 v[36:37], v[36:37], v[38:39]
	v_div_scale_f64 v[38:39], vcc, v[32:33], s[72:73], v[32:33]
	v_mul_f64 v[40:41], v[38:39], v[36:37]
	v_fma_f64 v[34:35], -v[34:35], v[40:41], v[38:39]
	s_nop 1
	v_div_fmas_f64 v[34:35], v[34:35], v[36:37], v[40:41]
	v_div_fixup_f64 v[32:33], v[34:35], s[72:73], v[32:33]
	v_div_scale_f64 v[34:35], vcc, s[12:13], s[12:13], v[28:29]
	v_rcp_f64_e32 v[36:37], v[34:35]
	v_add_f64 v[26:27], v[26:27], v[32:33]
	v_mul_f64 v[32:33], v[16:17], v[32:33]
	v_fma_f64 v[38:39], -v[34:35], v[36:37], 1.0
	v_fmac_f64_e32 v[36:37], v[36:37], v[38:39]
	v_fma_f64 v[38:39], -v[34:35], v[36:37], 1.0
	v_fmac_f64_e32 v[36:37], v[36:37], v[38:39]
	v_div_scale_f64 v[38:39], vcc, v[28:29], s[12:13], v[28:29]
	v_mul_f64 v[40:41], v[38:39], v[36:37]
	v_fma_f64 v[34:35], -v[34:35], v[40:41], v[38:39]
	s_nop 1
	v_div_fmas_f64 v[34:35], v[34:35], v[36:37], v[40:41]
	v_div_fixup_f64 v[28:29], v[34:35], s[12:13], v[28:29]
	s_mov_b32 s12, 0
	s_mov_b32 s13, 0xc0710000
	v_div_scale_f64 v[34:35], vcc, s[12:13], s[12:13], v[32:33]
	v_rcp_f64_e32 v[36:37], v[34:35]
	v_add_f64 v[30:31], v[30:31], v[28:29]
	v_mul_f64 v[28:29], v[16:17], v[28:29]
	v_fma_f64 v[38:39], -v[34:35], v[36:37], 1.0
	v_fmac_f64_e32 v[36:37], v[36:37], v[38:39]
	v_fma_f64 v[38:39], -v[34:35], v[36:37], 1.0
	v_fmac_f64_e32 v[36:37], v[36:37], v[38:39]
	v_div_scale_f64 v[38:39], vcc, v[32:33], s[12:13], v[32:33]
	v_mul_f64 v[40:41], v[38:39], v[36:37]
	v_fma_f64 v[34:35], -v[34:35], v[40:41], v[38:39]
	s_nop 1
	v_div_fmas_f64 v[34:35], v[34:35], v[36:37], v[40:41]
	v_div_fixup_f64 v[32:33], v[34:35], s[12:13], v[32:33]
	s_mov_b32 s12, 0
	s_mov_b32 s13, 0xc0732000
	v_div_scale_f64 v[34:35], vcc, s[12:13], s[12:13], v[28:29]
	v_rcp_f64_e32 v[36:37], v[34:35]
	v_add_f64 v[26:27], v[26:27], v[32:33]
	v_mul_f64 v[32:33], v[16:17], v[32:33]
	v_fma_f64 v[38:39], -v[34:35], v[36:37], 1.0
	v_fmac_f64_e32 v[36:37], v[36:37], v[38:39]
	v_fma_f64 v[38:39], -v[34:35], v[36:37], 1.0
	v_fmac_f64_e32 v[36:37], v[36:37], v[38:39]
	v_div_scale_f64 v[38:39], vcc, v[28:29], s[12:13], v[28:29]
	v_mul_f64 v[40:41], v[38:39], v[36:37]
	v_fma_f64 v[34:35], -v[34:35], v[40:41], v[38:39]
	s_nop 1
	v_div_fmas_f64 v[34:35], v[34:35], v[36:37], v[40:41]
	v_div_fixup_f64 v[28:29], v[34:35], s[12:13], v[28:29]
	v_div_scale_f64 v[34:35], vcc, s[42:43], s[42:43], v[32:33]
	v_rcp_f64_e32 v[36:37], v[34:35]
	v_add_f64 v[30:31], v[30:31], v[28:29]
	v_mul_f64 v[28:29], v[16:17], v[28:29]
	v_readlane_b32 s12, v240, 33
	v_fma_f64 v[38:39], -v[34:35], v[36:37], 1.0
	v_fmac_f64_e32 v[36:37], v[36:37], v[38:39]
	v_fma_f64 v[38:39], -v[34:35], v[36:37], 1.0
	v_fmac_f64_e32 v[36:37], v[36:37], v[38:39]
	v_div_scale_f64 v[38:39], vcc, v[32:33], s[42:43], v[32:33]
	v_mul_f64 v[40:41], v[38:39], v[36:37]
	v_fma_f64 v[34:35], -v[34:35], v[40:41], v[38:39]
	v_readlane_b32 s13, v240, 34
	s_nop 0
	v_div_fmas_f64 v[34:35], v[34:35], v[36:37], v[40:41]
	v_div_fixup_f64 v[32:33], v[34:35], s[42:43], v[32:33]
	v_div_scale_f64 v[34:35], vcc, s[2:3], s[2:3], v[28:29]
	v_rcp_f64_e32 v[36:37], v[34:35]
	v_add_f64 v[26:27], v[26:27], v[32:33]
	v_mul_f64 v[32:33], v[16:17], v[32:33]
	v_fma_f64 v[38:39], -v[34:35], v[36:37], 1.0
	v_fmac_f64_e32 v[36:37], v[36:37], v[38:39]
	v_fma_f64 v[38:39], -v[34:35], v[36:37], 1.0
	v_fmac_f64_e32 v[36:37], v[36:37], v[38:39]
	v_div_scale_f64 v[38:39], vcc, v[28:29], s[2:3], v[28:29]
	v_mul_f64 v[40:41], v[38:39], v[36:37]
	v_fma_f64 v[34:35], -v[34:35], v[40:41], v[38:39]
	s_nop 1
	v_div_fmas_f64 v[34:35], v[34:35], v[36:37], v[40:41]
	v_div_fixup_f64 v[28:29], v[34:35], s[2:3], v[28:29]
	v_div_scale_f64 v[34:35], vcc, s[34:35], s[34:35], v[32:33]
	v_rcp_f64_e32 v[36:37], v[34:35]
	v_add_f64 v[30:31], v[30:31], v[28:29]
	v_mul_f64 v[28:29], v[16:17], v[28:29]
	v_fma_f64 v[38:39], -v[34:35], v[36:37], 1.0
	v_fmac_f64_e32 v[36:37], v[36:37], v[38:39]
	v_fma_f64 v[38:39], -v[34:35], v[36:37], 1.0
	v_fmac_f64_e32 v[36:37], v[36:37], v[38:39]
	v_div_scale_f64 v[38:39], vcc, v[32:33], s[34:35], v[32:33]
	v_mul_f64 v[40:41], v[38:39], v[36:37]
	v_fma_f64 v[34:35], -v[34:35], v[40:41], v[38:39]
	s_nop 1
	v_div_fmas_f64 v[34:35], v[34:35], v[36:37], v[40:41]
	v_div_fixup_f64 v[32:33], v[34:35], s[34:35], v[32:33]
	v_div_scale_f64 v[34:35], vcc, s[38:39], s[38:39], v[28:29]
	v_rcp_f64_e32 v[36:37], v[34:35]
	v_add_f64 v[26:27], v[26:27], v[32:33]
	v_mul_f64 v[32:33], v[16:17], v[32:33]
	v_fma_f64 v[38:39], -v[34:35], v[36:37], 1.0
	v_fmac_f64_e32 v[36:37], v[36:37], v[38:39]
	v_fma_f64 v[38:39], -v[34:35], v[36:37], 1.0
	v_fmac_f64_e32 v[36:37], v[36:37], v[38:39]
	v_div_scale_f64 v[38:39], vcc, v[28:29], s[38:39], v[28:29]
	v_mul_f64 v[40:41], v[38:39], v[36:37]
	v_fma_f64 v[34:35], -v[34:35], v[40:41], v[38:39]
	s_nop 1
	v_div_fmas_f64 v[34:35], v[34:35], v[36:37], v[40:41]
	v_div_fixup_f64 v[28:29], v[34:35], s[38:39], v[28:29]
	v_div_scale_f64 v[34:35], vcc, s[74:75], s[74:75], v[32:33]
	v_rcp_f64_e32 v[36:37], v[34:35]
	v_add_f64 v[30:31], v[30:31], v[28:29]
	v_mul_f64 v[28:29], v[16:17], v[28:29]
	v_fma_f64 v[38:39], -v[34:35], v[36:37], 1.0
	v_fmac_f64_e32 v[36:37], v[36:37], v[38:39]
	v_fma_f64 v[38:39], -v[34:35], v[36:37], 1.0
	v_fmac_f64_e32 v[36:37], v[36:37], v[38:39]
	v_div_scale_f64 v[38:39], vcc, v[32:33], s[74:75], v[32:33]
	v_mul_f64 v[40:41], v[38:39], v[36:37]
	v_fma_f64 v[34:35], -v[34:35], v[40:41], v[38:39]
	s_nop 1
	v_div_fmas_f64 v[34:35], v[34:35], v[36:37], v[40:41]
	v_div_fixup_f64 v[32:33], v[34:35], s[74:75], v[32:33]
	v_div_scale_f64 v[34:35], vcc, s[76:77], s[76:77], v[28:29]
	v_rcp_f64_e32 v[36:37], v[34:35]
	v_add_f64 v[26:27], v[26:27], v[32:33]
	v_mul_f64 v[32:33], v[16:17], v[32:33]
	v_fma_f64 v[38:39], -v[34:35], v[36:37], 1.0
	v_fmac_f64_e32 v[36:37], v[36:37], v[38:39]
	v_fma_f64 v[38:39], -v[34:35], v[36:37], 1.0
	v_fmac_f64_e32 v[36:37], v[36:37], v[38:39]
	v_div_scale_f64 v[38:39], vcc, v[28:29], s[76:77], v[28:29]
	v_mul_f64 v[40:41], v[38:39], v[36:37]
	v_fma_f64 v[34:35], -v[34:35], v[40:41], v[38:39]
	s_nop 1
	v_div_fmas_f64 v[34:35], v[34:35], v[36:37], v[40:41]
	v_div_fixup_f64 v[28:29], v[34:35], s[76:77], v[28:29]
	v_div_scale_f64 v[34:35], vcc, s[80:81], s[80:81], v[32:33]
	v_rcp_f64_e32 v[36:37], v[34:35]
	v_add_f64 v[30:31], v[30:31], v[28:29]
	v_mul_f64 v[28:29], v[16:17], v[28:29]
	v_fma_f64 v[38:39], -v[34:35], v[36:37], 1.0
	v_fmac_f64_e32 v[36:37], v[36:37], v[38:39]
	v_fma_f64 v[38:39], -v[34:35], v[36:37], 1.0
	v_fmac_f64_e32 v[36:37], v[36:37], v[38:39]
	v_div_scale_f64 v[38:39], vcc, v[32:33], s[80:81], v[32:33]
	v_mul_f64 v[40:41], v[38:39], v[36:37]
	v_fma_f64 v[34:35], -v[34:35], v[40:41], v[38:39]
	s_nop 1
	v_div_fmas_f64 v[34:35], v[34:35], v[36:37], v[40:41]
	v_div_fixup_f64 v[32:33], v[34:35], s[80:81], v[32:33]
	v_div_scale_f64 v[34:35], vcc, s[82:83], s[82:83], v[28:29]
	v_rcp_f64_e32 v[36:37], v[34:35]
	v_add_f64 v[26:27], v[26:27], v[32:33]
	v_mul_f64 v[32:33], v[16:17], v[32:33]
	v_fma_f64 v[38:39], -v[34:35], v[36:37], 1.0
	v_fmac_f64_e32 v[36:37], v[36:37], v[38:39]
	v_fma_f64 v[38:39], -v[34:35], v[36:37], 1.0
	v_fmac_f64_e32 v[36:37], v[36:37], v[38:39]
	v_div_scale_f64 v[38:39], vcc, v[28:29], s[82:83], v[28:29]
	v_mul_f64 v[40:41], v[38:39], v[36:37]
	v_fma_f64 v[34:35], -v[34:35], v[40:41], v[38:39]
	s_nop 1
	v_div_fmas_f64 v[34:35], v[34:35], v[36:37], v[40:41]
	v_div_fixup_f64 v[28:29], v[34:35], s[82:83], v[28:29]
	v_div_scale_f64 v[34:35], vcc, s[84:85], s[84:85], v[32:33]
	v_rcp_f64_e32 v[36:37], v[34:35]
	v_add_f64 v[30:31], v[30:31], v[28:29]
	v_mul_f64 v[28:29], v[16:17], v[28:29]
	v_fma_f64 v[38:39], -v[34:35], v[36:37], 1.0
	v_fmac_f64_e32 v[36:37], v[36:37], v[38:39]
	v_fma_f64 v[38:39], -v[34:35], v[36:37], 1.0
	v_fmac_f64_e32 v[36:37], v[36:37], v[38:39]
	v_div_scale_f64 v[38:39], vcc, v[32:33], s[84:85], v[32:33]
	v_mul_f64 v[40:41], v[38:39], v[36:37]
	v_fma_f64 v[34:35], -v[34:35], v[40:41], v[38:39]
	s_nop 1
	v_div_fmas_f64 v[34:35], v[34:35], v[36:37], v[40:41]
	v_div_fixup_f64 v[32:33], v[34:35], s[84:85], v[32:33]
	v_div_scale_f64 v[34:35], vcc, s[86:87], s[86:87], v[28:29]
	v_rcp_f64_e32 v[36:37], v[34:35]
	v_mul_f64 v[16:17], v[16:17], v[32:33]
	v_add_f64 v[26:27], v[26:27], v[32:33]
	v_fma_f64 v[38:39], -v[34:35], v[36:37], 1.0
	v_fmac_f64_e32 v[36:37], v[36:37], v[38:39]
	v_fma_f64 v[38:39], -v[34:35], v[36:37], 1.0
	v_fmac_f64_e32 v[36:37], v[36:37], v[38:39]
	v_div_scale_f64 v[38:39], vcc, v[28:29], s[86:87], v[28:29]
	v_mul_f64 v[40:41], v[38:39], v[36:37]
	v_fma_f64 v[34:35], -v[34:35], v[40:41], v[38:39]
	s_nop 1
	v_div_fmas_f64 v[34:35], v[34:35], v[36:37], v[40:41]
	v_div_fixup_f64 v[28:29], v[34:35], s[86:87], v[28:29]
	v_add_f64 v[28:29], v[30:31], v[28:29]
	v_div_scale_f64 v[30:31], vcc, s[90:91], s[90:91], v[16:17]
	v_rcp_f64_e32 v[32:33], v[30:31]
	s_nop 0
	v_fma_f64 v[34:35], -v[30:31], v[32:33], 1.0
	v_fmac_f64_e32 v[32:33], v[32:33], v[34:35]
	v_fma_f64 v[34:35], -v[30:31], v[32:33], 1.0
	v_fmac_f64_e32 v[32:33], v[32:33], v[34:35]
	v_div_scale_f64 v[34:35], vcc, v[16:17], s[90:91], v[16:17]
	v_mul_f64 v[36:37], v[34:35], v[32:33]
	v_fma_f64 v[30:31], -v[30:31], v[36:37], v[34:35]
	s_nop 1
	v_div_fmas_f64 v[30:31], v[30:31], v[32:33], v[36:37]
	v_div_fixup_f64 v[16:17], v[30:31], s[90:91], v[16:17]
	v_add_f64 v[16:17], v[26:27], v[16:17]
	v_mul_f64 v[30:31], v[20:21], v[16:17]
	v_mul_f64 v[26:27], v[20:21], v[28:29]
	v_fma_f64 v[20:21], v[20:21], v[28:29], -1.0
	v_mul_f64 v[28:29], v[30:31], v[18:19]
	v_lshlrev_b64 v[32:33], 2, v[6:7]
	v_mul_f64 v[16:17], v[18:19], v[18:19]
	v_fmac_f64_e32 v[28:29], v[12:13], v[20:21]
	v_mul_f64 v[18:19], v[20:21], v[18:19]
	v_cvt_f32_f64_e32 v20, v[26:27]
	v_lshl_add_u64 v[34:35], s[12:13], 0, v[32:33]
	v_cvt_f32_f64_e32 v21, v[30:31]
	global_store_dwordx2 v[34:35], v[20:21], off
	v_mul_f64 v[20:21], v[30:31], v[30:31]
	v_fma_f64 v[20:21], v[26:27], v[26:27], -v[20:21]
	v_add_f64 v[26:27], v[26:27], v[26:27]
	v_mul_f64 v[26:27], v[26:27], v[30:31]
	v_fma_f64 v[18:19], v[12:13], v[30:31], -v[18:19]
	v_mul_f64 v[30:31], v[26:27], v[26:27]
	v_fma_f64 v[30:31], v[20:21], v[20:21], -v[30:31]
	v_add_f64 v[20:21], v[20:21], v[20:21]
	v_mul_f64 v[20:21], v[26:27], v[20:21]
	v_mul_f64 v[26:27], v[20:21], v[20:21]
	v_fma_f64 v[26:27], v[30:31], v[30:31], -v[26:27]
	v_add_f64 v[30:31], v[30:31], v[30:31]
	v_mul_f64 v[20:21], v[20:21], v[30:31]
	v_mul_f64 v[30:31], v[20:21], v[20:21]
	v_fma_f64 v[30:31], v[26:27], v[26:27], -v[30:31]
	v_add_f64 v[26:27], v[26:27], v[26:27]
	v_mul_f64 v[20:21], v[20:21], v[26:27]
	v_mul_f64 v[26:27], v[20:21], v[20:21]
	v_fma_f64 v[26:27], v[30:31], v[30:31], -v[26:27]
	v_add_f64 v[30:31], v[30:31], v[30:31]
	v_mul_f64 v[20:21], v[20:21], v[30:31]
	v_mul_f64 v[30:31], v[20:21], v[20:21]
	v_fmac_f64_e32 v[16:17], v[12:13], v[12:13]
	v_fma_f64 v[30:31], v[26:27], v[26:27], -v[30:31]
	v_add_f64 v[26:27], v[26:27], v[26:27]
	v_div_scale_f64 v[12:13], vcc, v[16:17], v[16:17], v[28:29]
	v_mul_f64 v[20:21], v[20:21], v[26:27]
	v_rcp_f64_e32 v[26:27], v[12:13]
	v_add_u32_e32 v36, 1, v6
	v_ashrrev_i32_e32 v37, 31, v36
	v_cvt_f32_f64_e32 v7, v[30:31]
	v_fma_f64 v[34:35], -v[12:13], v[26:27], 1.0
	v_fmac_f64_e32 v[26:27], v[26:27], v[34:35]
	v_fma_f64 v[34:35], -v[12:13], v[26:27], 1.0
	v_fmac_f64_e32 v[26:27], v[26:27], v[34:35]
	v_div_scale_f64 v[34:35], vcc, v[28:29], v[16:17], v[28:29]
	v_mul_f64 v[38:39], v[34:35], v[26:27]
	v_fma_f64 v[12:13], -v[12:13], v[38:39], v[34:35]
	v_readlane_b32 s12, v240, 1
	s_nop 0
	v_div_fmas_f64 v[12:13], v[12:13], v[26:27], v[38:39]
	v_lshl_add_u64 v[26:27], s[4:5], 0, v[32:33]
	global_store_dword v[26:27], v7, off
	v_cvt_f32_f64_e32 v7, v[20:21]
	v_lshl_add_u64 v[20:21], v[36:37], 2, s[4:5]
	global_store_dword v[20:21], v7, off
	v_lshl_add_u64 v[20:21], s[62:63], 0, v[10:11]
	v_div_fixup_f64 v[12:13], v[12:13], v[16:17], v[28:29]
	global_load_dwordx4 v[24:27], v[20:21], off offset:32
	global_load_dwordx4 v[28:31], v[20:21], off offset:48
	global_load_dwordx4 v[32:35], v[20:21], off
	global_load_dwordx4 v[36:39], v[20:21], off offset:16
	global_load_dwordx4 v[40:43], v[52:53], off offset:32
	global_load_dwordx4 v[44:47], v[52:53], off offset:48
	global_load_dwordx4 v[48:51], v[52:53], off
	s_nop 0
	global_load_dwordx4 v[52:55], v[52:53], off offset:16
	v_div_scale_f64 v[20:21], vcc, v[16:17], v[16:17], v[18:19]
	v_readlane_b32 s13, v240, 2
	s_add_u32 s62, s62, s46
	s_addc_u32 s63, s63, s47
	v_readlane_b32 s14, v240, 3
	v_readlane_b32 s15, v240, 4
	v_readlane_b32 s16, v240, 5
	v_readlane_b32 s17, v240, 6
	v_readlane_b32 s18, v240, 7
	v_readlane_b32 s19, v240, 8
	v_readlane_b32 s20, v240, 9
	v_readlane_b32 s21, v240, 10
	v_readlane_b32 s22, v240, 11
	v_readlane_b32 s23, v240, 12
	v_readlane_b32 s24, v240, 13
	v_readlane_b32 s25, v240, 14
	v_readlane_b32 s26, v240, 15
	v_readlane_b32 s27, v240, 16
	s_waitcnt vmcnt(6)
	v_cvt_pk_f16_f32 v31, v30, v31
	v_cvt_pk_f16_f32 v30, v28, v29
	v_cvt_pk_f16_f32 v29, v26, v27
	v_cvt_pk_f16_f32 v28, v24, v25
	s_waitcnt vmcnt(2)
	v_cvt_pk_f16_f32 v27, v46, v47
	v_cvt_pk_f16_f32 v26, v44, v45
	v_cvt_pk_f16_f32 v25, v42, v43
	v_cvt_pk_f16_f32 v24, v40, v41
	global_store_dwordx4 v[58:59], v[24:27], off offset:48
	global_store_dwordx4 v[58:59], v[28:31], off offset:16
	v_cvt_pk_f16_f32 v39, v38, v39
	v_rcp_f64_e32 v[24:25], v[20:21]
	v_cvt_pk_f16_f32 v38, v36, v37
	v_cvt_pk_f16_f32 v37, v34, v35
	v_cvt_pk_f16_f32 v36, v32, v33
	v_fma_f64 v[26:27], -v[20:21], v[24:25], 1.0
	v_fmac_f64_e32 v[24:25], v[24:25], v[26:27]
	v_fma_f64 v[26:27], -v[20:21], v[24:25], 1.0
	v_fmac_f64_e32 v[24:25], v[24:25], v[26:27]
	v_div_scale_f64 v[26:27], vcc, v[18:19], v[16:17], v[18:19]
	v_mul_f64 v[28:29], v[26:27], v[24:25]
	v_fma_f64 v[20:21], -v[20:21], v[28:29], v[26:27]
	s_waitcnt vmcnt(2)
	v_cvt_pk_f16_f32 v35, v54, v55
	v_div_fmas_f64 v[20:21], v[20:21], v[24:25], v[28:29]
	v_div_fixup_f64 v[18:19], v[20:21], v[16:17], v[18:19]
	v_lshlrev_b64 v[20:21], 12, v[14:15]
	v_lshl_or_b32 v20, v176, 2, v20
	v_lshl_add_u64 v[14:15], s[66:67], 0, v[20:21]
	global_load_dword v7, v[14:15], off
	v_lshl_add_u64 v[20:21], s[12:13], 0, v[20:21]
	v_lshl_add_u64 v[16:17], v[4:5], 0, v[56:57]
	v_readlane_b32 s12, v240, 38
	v_readlane_b32 s13, v240, 39
	v_cvt_pk_f16_f32 v34, v52, v53
	v_add_u32_e32 v0, s12, v0
	v_readlane_b32 s12, v240, 35
	v_cvt_pk_f16_f32 v33, v50, v51
	v_cvt_pk_f16_f32 v32, v48, v49
	v_add_u32_e32 v6, s12, v6
	v_readlane_b32 s12, v240, 36
	v_readlane_b32 s13, v240, 37
	global_store_dwordx4 v[58:59], v[36:39], off
	global_store_dwordx4 v[58:59], v[32:35], off offset:32
	v_lshl_add_u64 v[8:9], v[8:9], 0, s[12:13]
	s_waitcnt vmcnt(2)
	v_cvt_f64_f32_e32 v[24:25], v7
	global_load_dword v136, v[20:21], off
	global_load_dword v121, v[14:15], off offset:256
	global_load_dword v122, v[14:15], off offset:512
	global_load_dword v123, v[14:15], off offset:768
	global_load_dword v124, v[14:15], off offset:1024
	global_load_dword v125, v[14:15], off offset:1280
	global_load_dword v126, v[14:15], off offset:1536
	global_load_dword v127, v[14:15], off offset:1792
	global_load_dword v128, v[14:15], off offset:2048
	global_load_dword v129, v[14:15], off offset:2304
	global_load_dword v130, v[14:15], off offset:2560
	global_load_dword v131, v[14:15], off offset:2816
	global_load_dword v132, v[14:15], off offset:3072
	global_load_dword v133, v[14:15], off offset:3328
	global_load_dword v134, v[14:15], off offset:3584
	global_load_dword v135, v[14:15], off offset:3840
	global_load_dword v137, v[20:21], off offset:256
	global_load_dword v138, v[20:21], off offset:512
	global_load_dword v139, v[20:21], off offset:768
	global_load_dword v140, v[20:21], off offset:1024
	global_load_dword v141, v[20:21], off offset:1280
	global_load_dword v142, v[20:21], off offset:1536
	global_load_dword v143, v[20:21], off offset:1792
	global_load_dword v144, v[20:21], off offset:2048
	global_load_dword v145, v[20:21], off offset:2304
	global_load_dword v146, v[20:21], off offset:2560
	global_load_dword v147, v[20:21], off offset:2816
	global_load_dword v148, v[20:21], off offset:3072
	global_load_dword v149, v[20:21], off offset:3328
	global_load_dword v150, v[20:21], off offset:3584
	global_load_dword v151, v[20:21], off offset:3840
	s_waitcnt vmcnt(0)
	v_cvt_f64_f32_e32 v[26:27], v136
	v_mul_f64 v[28:29], v[18:19], v[26:27]
	v_fma_f64 v[28:29], v[12:13], v[24:25], -v[28:29]
	v_mul_f64 v[26:27], v[12:13], v[26:27]
	v_fmac_f64_e32 v[26:27], v[18:19], v[24:25]
	v_ldexp_f64 v[24:25], v[28:29], 10
	v_and_or_b32 v7, v25, s33, v24
	v_cmp_ne_u32_e32 vcc, 0, v7
	v_lshrrev_b32_e32 v24, 8, v25
	v_bfe_u32 v28, v25, 20, 11
	v_cndmask_b32_e64 v7, 0, 1, vcc
	v_and_or_b32 v7, v24, s92, v7
	v_sub_u32_e32 v29, 0x3f1, v28
	v_or_b32_e32 v24, 0x1000, v7
	v_med3_i32 v29, v29, 0, 13
	v_lshrrev_b32_e32 v30, v29, v24
	v_lshlrev_b32_e32 v29, v29, v30
	v_cmp_ne_u32_e32 vcc, v29, v24
	v_add_u32_e32 v28, 0xfffffc10, v28
	v_lshl_or_b32 v29, v28, 12, v7
	v_cndmask_b32_e64 v24, 0, 1, vcc
	v_or_b32_e32 v24, v30, v24
	v_cmp_gt_i32_e32 vcc, 1, v28
	s_nop 1
	v_cndmask_b32_e32 v24, v29, v24, vcc
	v_and_b32_e32 v29, 7, v24
	v_cmp_lt_i32_e32 vcc, 5, v29
	v_lshrrev_b32_e32 v24, 2, v24
	s_nop 0
	v_cndmask_b32_e64 v30, 0, 1, vcc
	v_cmp_eq_u32_e32 vcc, 3, v29
	s_nop 1
	v_cndmask_b32_e64 v29, 0, 1, vcc
	v_or_b32_e32 v29, v29, v30
	v_add_u32_e32 v24, v24, v29
	v_cmp_gt_i32_e32 vcc, 31, v28
	s_nop 1
	v_cndmask_b32_e32 v24, v22, v24, vcc
	v_cmp_ne_u32_e32 vcc, 0, v7
	s_nop 1
	v_cndmask_b32_e32 v7, v22, v23, vcc
	v_cmp_eq_u32_e32 vcc, s93, v28
	s_nop 1
	v_cndmask_b32_e32 v7, v24, v7, vcc
	v_lshrrev_b32_e32 v24, 16, v25
	v_and_or_b32 v7, v24, s70, v7
	v_ldexp_f64 v[24:25], -v[26:27], 10
	v_and_or_b32 v24, v25, s33, v24
	v_cmp_ne_u32_e32 vcc, 0, v24
	v_lshrrev_b32_e32 v26, 8, v25
	v_bfe_u32 v27, v25, 20, 11
	v_cndmask_b32_e64 v24, 0, 1, vcc
	v_and_or_b32 v24, v26, s92, v24
	v_sub_u32_e32 v28, 0x3f1, v27
	v_or_b32_e32 v26, 0x1000, v24
	v_med3_i32 v28, v28, 0, 13
	v_lshrrev_b32_e32 v29, v28, v26
	v_lshlrev_b32_e32 v28, v28, v29
	v_cmp_ne_u32_e32 vcc, v28, v26
	v_add_u32_e32 v27, 0xfffffc10, v27
	v_lshl_or_b32 v28, v27, 12, v24
	v_cndmask_b32_e64 v26, 0, 1, vcc
	v_or_b32_e32 v26, v29, v26
	v_cmp_gt_i32_e32 vcc, 1, v27
	v_lshrrev_b32_e32 v25, 16, v25
	s_nop 0
	v_cndmask_b32_e32 v26, v28, v26, vcc
	v_and_b32_e32 v28, 7, v26
	v_cmp_lt_i32_e32 vcc, 5, v28
	v_lshrrev_b32_e32 v26, 2, v26
	s_nop 0
	v_cndmask_b32_e64 v29, 0, 1, vcc
	v_cmp_eq_u32_e32 vcc, 3, v28
	s_nop 1
	v_cndmask_b32_e64 v28, 0, 1, vcc
	v_or_b32_e32 v28, v28, v29
	v_add_u32_e32 v26, v26, v28
	v_cmp_gt_i32_e32 vcc, 31, v27
	s_nop 1
	v_cndmask_b32_e32 v26, v22, v26, vcc
	v_cmp_ne_u32_e32 vcc, 0, v24
	s_nop 1
	v_cndmask_b32_e32 v24, v22, v23, vcc
	v_cmp_eq_u32_e32 vcc, s93, v27
	s_nop 1
	v_cndmask_b32_e32 v24, v26, v24, vcc
	v_and_or_b32 v24, v25, s70, v24
	v_perm_b32 v7, v24, v7, s71
	global_store_dword v[16:17], v7, off
	v_cvt_f64_f32_e32 v[24:25], v121
	v_cvt_f64_f32_e32 v[26:27], v137
	v_mul_f64 v[28:29], v[18:19], v[26:27]
	v_fma_f64 v[28:29], v[12:13], v[24:25], -v[28:29]
	v_mul_f64 v[26:27], v[12:13], v[26:27]
	v_fmac_f64_e32 v[26:27], v[18:19], v[24:25]
	v_ldexp_f64 v[24:25], v[28:29], 10
	v_and_or_b32 v7, v25, s33, v24
	v_cmp_ne_u32_e32 vcc, 0, v7
	v_lshrrev_b32_e32 v24, 8, v25
	v_bfe_u32 v28, v25, 20, 11
	v_cndmask_b32_e64 v7, 0, 1, vcc
	v_and_or_b32 v7, v24, s92, v7
	v_sub_u32_e32 v29, 0x3f1, v28
	v_or_b32_e32 v24, 0x1000, v7
	v_med3_i32 v29, v29, 0, 13
	v_lshrrev_b32_e32 v30, v29, v24
	v_lshlrev_b32_e32 v29, v29, v30
	v_cmp_ne_u32_e32 vcc, v29, v24
	v_add_u32_e32 v28, 0xfffffc10, v28
	v_lshl_or_b32 v29, v28, 12, v7
	v_cndmask_b32_e64 v24, 0, 1, vcc
	v_or_b32_e32 v24, v30, v24
	v_cmp_gt_i32_e32 vcc, 1, v28
	s_nop 1
	v_cndmask_b32_e32 v24, v29, v24, vcc
	v_and_b32_e32 v29, 7, v24
	v_cmp_lt_i32_e32 vcc, 5, v29
	v_lshrrev_b32_e32 v24, 2, v24
	s_nop 0
	v_cndmask_b32_e64 v30, 0, 1, vcc
	v_cmp_eq_u32_e32 vcc, 3, v29
	s_nop 1
	v_cndmask_b32_e64 v29, 0, 1, vcc
	v_or_b32_e32 v29, v29, v30
	v_add_u32_e32 v24, v24, v29
	v_cmp_gt_i32_e32 vcc, 31, v28
	s_nop 1
	v_cndmask_b32_e32 v24, v22, v24, vcc
	v_cmp_ne_u32_e32 vcc, 0, v7
	s_nop 1
	v_cndmask_b32_e32 v7, v22, v23, vcc
	v_cmp_eq_u32_e32 vcc, s93, v28
	s_nop 1
	v_cndmask_b32_e32 v7, v24, v7, vcc
	v_lshrrev_b32_e32 v24, 16, v25
	v_and_or_b32 v7, v24, s70, v7
	v_ldexp_f64 v[24:25], -v[26:27], 10
	v_and_or_b32 v24, v25, s33, v24
	v_cmp_ne_u32_e32 vcc, 0, v24
	v_lshrrev_b32_e32 v26, 8, v25
	v_bfe_u32 v27, v25, 20, 11
	v_cndmask_b32_e64 v24, 0, 1, vcc
	v_and_or_b32 v24, v26, s92, v24
	v_sub_u32_e32 v28, 0x3f1, v27
	v_or_b32_e32 v26, 0x1000, v24
	v_med3_i32 v28, v28, 0, 13
	v_lshrrev_b32_e32 v29, v28, v26
	v_lshlrev_b32_e32 v28, v28, v29
	v_cmp_ne_u32_e32 vcc, v28, v26
	v_add_u32_e32 v27, 0xfffffc10, v27
	v_lshl_or_b32 v28, v27, 12, v24
	v_cndmask_b32_e64 v26, 0, 1, vcc
	v_or_b32_e32 v26, v29, v26
	v_cmp_gt_i32_e32 vcc, 1, v27
	v_lshrrev_b32_e32 v25, 16, v25
	s_nop 0
	v_cndmask_b32_e32 v26, v28, v26, vcc
	v_and_b32_e32 v28, 7, v26
	v_cmp_lt_i32_e32 vcc, 5, v28
	v_lshrrev_b32_e32 v26, 2, v26
	s_nop 0
	v_cndmask_b32_e64 v29, 0, 1, vcc
	v_cmp_eq_u32_e32 vcc, 3, v28
	s_nop 1
	v_cndmask_b32_e64 v28, 0, 1, vcc
	v_or_b32_e32 v28, v28, v29
	v_add_u32_e32 v26, v26, v28
	v_cmp_gt_i32_e32 vcc, 31, v27
	s_nop 1
	v_cndmask_b32_e32 v26, v22, v26, vcc
	v_cmp_ne_u32_e32 vcc, 0, v24
	s_nop 1
	v_cndmask_b32_e32 v24, v22, v23, vcc
	v_cmp_eq_u32_e32 vcc, s93, v27
	s_nop 1
	v_cndmask_b32_e32 v24, v26, v24, vcc
	v_and_or_b32 v24, v25, s70, v24
	v_perm_b32 v7, v24, v7, s71
	global_store_dword v[16:17], v7, off offset:256
	v_cvt_f64_f32_e32 v[24:25], v122
	v_cvt_f64_f32_e32 v[26:27], v138
	v_mul_f64 v[28:29], v[18:19], v[26:27]
	v_fma_f64 v[28:29], v[12:13], v[24:25], -v[28:29]
	v_mul_f64 v[26:27], v[12:13], v[26:27]
	v_fmac_f64_e32 v[26:27], v[18:19], v[24:25]
	v_ldexp_f64 v[24:25], v[28:29], 10
	v_and_or_b32 v7, v25, s33, v24
	v_cmp_ne_u32_e32 vcc, 0, v7
	v_lshrrev_b32_e32 v24, 8, v25
	v_bfe_u32 v28, v25, 20, 11
	v_cndmask_b32_e64 v7, 0, 1, vcc
	v_and_or_b32 v7, v24, s92, v7
	v_sub_u32_e32 v29, 0x3f1, v28
	v_or_b32_e32 v24, 0x1000, v7
	v_med3_i32 v29, v29, 0, 13
	v_lshrrev_b32_e32 v30, v29, v24
	v_lshlrev_b32_e32 v29, v29, v30
	v_cmp_ne_u32_e32 vcc, v29, v24
	v_add_u32_e32 v28, 0xfffffc10, v28
	v_lshl_or_b32 v29, v28, 12, v7
	v_cndmask_b32_e64 v24, 0, 1, vcc
	v_or_b32_e32 v24, v30, v24
	v_cmp_gt_i32_e32 vcc, 1, v28
	s_nop 1
	v_cndmask_b32_e32 v24, v29, v24, vcc
	v_and_b32_e32 v29, 7, v24
	v_cmp_lt_i32_e32 vcc, 5, v29
	v_lshrrev_b32_e32 v24, 2, v24
	s_nop 0
	v_cndmask_b32_e64 v30, 0, 1, vcc
	v_cmp_eq_u32_e32 vcc, 3, v29
	s_nop 1
	v_cndmask_b32_e64 v29, 0, 1, vcc
	v_or_b32_e32 v29, v29, v30
	v_add_u32_e32 v24, v24, v29
	v_cmp_gt_i32_e32 vcc, 31, v28
	s_nop 1
	v_cndmask_b32_e32 v24, v22, v24, vcc
	v_cmp_ne_u32_e32 vcc, 0, v7
	s_nop 1
	v_cndmask_b32_e32 v7, v22, v23, vcc
	v_cmp_eq_u32_e32 vcc, s93, v28
	s_nop 1
	v_cndmask_b32_e32 v7, v24, v7, vcc
	v_lshrrev_b32_e32 v24, 16, v25
	v_and_or_b32 v7, v24, s70, v7
	v_ldexp_f64 v[24:25], -v[26:27], 10
	v_and_or_b32 v24, v25, s33, v24
	v_cmp_ne_u32_e32 vcc, 0, v24
	v_lshrrev_b32_e32 v26, 8, v25
	v_bfe_u32 v27, v25, 20, 11
	v_cndmask_b32_e64 v24, 0, 1, vcc
	v_and_or_b32 v24, v26, s92, v24
	v_sub_u32_e32 v28, 0x3f1, v27
	v_or_b32_e32 v26, 0x1000, v24
	v_med3_i32 v28, v28, 0, 13
	v_lshrrev_b32_e32 v29, v28, v26
	v_lshlrev_b32_e32 v28, v28, v29
	v_cmp_ne_u32_e32 vcc, v28, v26
	v_add_u32_e32 v27, 0xfffffc10, v27
	v_lshl_or_b32 v28, v27, 12, v24
	v_cndmask_b32_e64 v26, 0, 1, vcc
	v_or_b32_e32 v26, v29, v26
	v_cmp_gt_i32_e32 vcc, 1, v27
	v_lshrrev_b32_e32 v25, 16, v25
	s_nop 0
	v_cndmask_b32_e32 v26, v28, v26, vcc
	v_and_b32_e32 v28, 7, v26
	v_cmp_lt_i32_e32 vcc, 5, v28
	v_lshrrev_b32_e32 v26, 2, v26
	s_nop 0
	v_cndmask_b32_e64 v29, 0, 1, vcc
	v_cmp_eq_u32_e32 vcc, 3, v28
	s_nop 1
	v_cndmask_b32_e64 v28, 0, 1, vcc
	v_or_b32_e32 v28, v28, v29
	v_add_u32_e32 v26, v26, v28
	v_cmp_gt_i32_e32 vcc, 31, v27
	s_nop 1
	v_cndmask_b32_e32 v26, v22, v26, vcc
	v_cmp_ne_u32_e32 vcc, 0, v24
	s_nop 1
	v_cndmask_b32_e32 v24, v22, v23, vcc
	v_cmp_eq_u32_e32 vcc, s93, v27
	s_nop 1
	v_cndmask_b32_e32 v24, v26, v24, vcc
	v_and_or_b32 v24, v25, s70, v24
	v_perm_b32 v7, v24, v7, s71
	global_store_dword v[16:17], v7, off offset:512
	v_cvt_f64_f32_e32 v[24:25], v123
	v_cvt_f64_f32_e32 v[26:27], v139
	v_mul_f64 v[28:29], v[18:19], v[26:27]
	v_fma_f64 v[28:29], v[12:13], v[24:25], -v[28:29]
	v_mul_f64 v[26:27], v[12:13], v[26:27]
	v_fmac_f64_e32 v[26:27], v[18:19], v[24:25]
	v_ldexp_f64 v[24:25], v[28:29], 10
	v_and_or_b32 v7, v25, s33, v24
	v_cmp_ne_u32_e32 vcc, 0, v7
	v_lshrrev_b32_e32 v24, 8, v25
	v_bfe_u32 v28, v25, 20, 11
	v_cndmask_b32_e64 v7, 0, 1, vcc
	v_and_or_b32 v7, v24, s92, v7
	v_sub_u32_e32 v29, 0x3f1, v28
	v_or_b32_e32 v24, 0x1000, v7
	v_med3_i32 v29, v29, 0, 13
	v_lshrrev_b32_e32 v30, v29, v24
	v_lshlrev_b32_e32 v29, v29, v30
	v_cmp_ne_u32_e32 vcc, v29, v24
	v_add_u32_e32 v28, 0xfffffc10, v28
	v_lshl_or_b32 v29, v28, 12, v7
	v_cndmask_b32_e64 v24, 0, 1, vcc
	v_or_b32_e32 v24, v30, v24
	v_cmp_gt_i32_e32 vcc, 1, v28
	s_nop 1
	v_cndmask_b32_e32 v24, v29, v24, vcc
	v_and_b32_e32 v29, 7, v24
	v_cmp_lt_i32_e32 vcc, 5, v29
	v_lshrrev_b32_e32 v24, 2, v24
	s_nop 0
	v_cndmask_b32_e64 v30, 0, 1, vcc
	v_cmp_eq_u32_e32 vcc, 3, v29
	s_nop 1
	v_cndmask_b32_e64 v29, 0, 1, vcc
	v_or_b32_e32 v29, v29, v30
	v_add_u32_e32 v24, v24, v29
	v_cmp_gt_i32_e32 vcc, 31, v28
	s_nop 1
	v_cndmask_b32_e32 v24, v22, v24, vcc
	v_cmp_ne_u32_e32 vcc, 0, v7
	s_nop 1
	v_cndmask_b32_e32 v7, v22, v23, vcc
	v_cmp_eq_u32_e32 vcc, s93, v28
	s_nop 1
	v_cndmask_b32_e32 v7, v24, v7, vcc
	v_lshrrev_b32_e32 v24, 16, v25
	v_and_or_b32 v7, v24, s70, v7
	v_ldexp_f64 v[24:25], -v[26:27], 10
	v_and_or_b32 v24, v25, s33, v24
	v_cmp_ne_u32_e32 vcc, 0, v24
	v_lshrrev_b32_e32 v26, 8, v25
	v_bfe_u32 v27, v25, 20, 11
	v_cndmask_b32_e64 v24, 0, 1, vcc
	v_and_or_b32 v24, v26, s92, v24
	v_sub_u32_e32 v28, 0x3f1, v27
	v_or_b32_e32 v26, 0x1000, v24
	v_med3_i32 v28, v28, 0, 13
	v_lshrrev_b32_e32 v29, v28, v26
	v_lshlrev_b32_e32 v28, v28, v29
	v_cmp_ne_u32_e32 vcc, v28, v26
	v_add_u32_e32 v27, 0xfffffc10, v27
	v_lshl_or_b32 v28, v27, 12, v24
	v_cndmask_b32_e64 v26, 0, 1, vcc
	v_or_b32_e32 v26, v29, v26
	v_cmp_gt_i32_e32 vcc, 1, v27
	v_lshrrev_b32_e32 v25, 16, v25
	s_nop 0
	v_cndmask_b32_e32 v26, v28, v26, vcc
	v_and_b32_e32 v28, 7, v26
	v_cmp_lt_i32_e32 vcc, 5, v28
	v_lshrrev_b32_e32 v26, 2, v26
	s_nop 0
	v_cndmask_b32_e64 v29, 0, 1, vcc
	v_cmp_eq_u32_e32 vcc, 3, v28
	s_nop 1
	v_cndmask_b32_e64 v28, 0, 1, vcc
	v_or_b32_e32 v28, v28, v29
	v_add_u32_e32 v26, v26, v28
	v_cmp_gt_i32_e32 vcc, 31, v27
	s_nop 1
	v_cndmask_b32_e32 v26, v22, v26, vcc
	v_cmp_ne_u32_e32 vcc, 0, v24
	s_nop 1
	v_cndmask_b32_e32 v24, v22, v23, vcc
	v_cmp_eq_u32_e32 vcc, s93, v27
	s_nop 1
	v_cndmask_b32_e32 v24, v26, v24, vcc
	v_and_or_b32 v24, v25, s70, v24
	v_perm_b32 v7, v24, v7, s71
	global_store_dword v[16:17], v7, off offset:768
	v_cvt_f64_f32_e32 v[24:25], v124
	v_cvt_f64_f32_e32 v[26:27], v140
	v_mul_f64 v[28:29], v[18:19], v[26:27]
	v_fma_f64 v[28:29], v[12:13], v[24:25], -v[28:29]
	v_mul_f64 v[26:27], v[12:13], v[26:27]
	v_fmac_f64_e32 v[26:27], v[18:19], v[24:25]
	v_ldexp_f64 v[24:25], v[28:29], 10
	v_and_or_b32 v7, v25, s33, v24
	v_cmp_ne_u32_e32 vcc, 0, v7
	v_lshrrev_b32_e32 v24, 8, v25
	v_bfe_u32 v28, v25, 20, 11
	v_cndmask_b32_e64 v7, 0, 1, vcc
	v_and_or_b32 v7, v24, s92, v7
	v_sub_u32_e32 v29, 0x3f1, v28
	v_or_b32_e32 v24, 0x1000, v7
	v_med3_i32 v29, v29, 0, 13
	v_lshrrev_b32_e32 v30, v29, v24
	v_lshlrev_b32_e32 v29, v29, v30
	v_cmp_ne_u32_e32 vcc, v29, v24
	v_add_u32_e32 v28, 0xfffffc10, v28
	v_lshl_or_b32 v29, v28, 12, v7
	v_cndmask_b32_e64 v24, 0, 1, vcc
	v_or_b32_e32 v24, v30, v24
	v_cmp_gt_i32_e32 vcc, 1, v28
	s_nop 1
	v_cndmask_b32_e32 v24, v29, v24, vcc
	v_and_b32_e32 v29, 7, v24
	v_cmp_lt_i32_e32 vcc, 5, v29
	v_lshrrev_b32_e32 v24, 2, v24
	s_nop 0
	v_cndmask_b32_e64 v30, 0, 1, vcc
	v_cmp_eq_u32_e32 vcc, 3, v29
	s_nop 1
	v_cndmask_b32_e64 v29, 0, 1, vcc
	v_or_b32_e32 v29, v29, v30
	v_add_u32_e32 v24, v24, v29
	v_cmp_gt_i32_e32 vcc, 31, v28
	s_nop 1
	v_cndmask_b32_e32 v24, v22, v24, vcc
	v_cmp_ne_u32_e32 vcc, 0, v7
	s_nop 1
	v_cndmask_b32_e32 v7, v22, v23, vcc
	v_cmp_eq_u32_e32 vcc, s93, v28
	s_nop 1
	v_cndmask_b32_e32 v7, v24, v7, vcc
	v_lshrrev_b32_e32 v24, 16, v25
	v_and_or_b32 v7, v24, s70, v7
	v_ldexp_f64 v[24:25], -v[26:27], 10
	v_and_or_b32 v24, v25, s33, v24
	v_cmp_ne_u32_e32 vcc, 0, v24
	v_lshrrev_b32_e32 v26, 8, v25
	v_bfe_u32 v27, v25, 20, 11
	v_cndmask_b32_e64 v24, 0, 1, vcc
	v_and_or_b32 v24, v26, s92, v24
	v_sub_u32_e32 v28, 0x3f1, v27
	v_or_b32_e32 v26, 0x1000, v24
	v_med3_i32 v28, v28, 0, 13
	v_lshrrev_b32_e32 v29, v28, v26
	v_lshlrev_b32_e32 v28, v28, v29
	v_cmp_ne_u32_e32 vcc, v28, v26
	v_add_u32_e32 v27, 0xfffffc10, v27
	v_lshl_or_b32 v28, v27, 12, v24
	v_cndmask_b32_e64 v26, 0, 1, vcc
	v_or_b32_e32 v26, v29, v26
	v_cmp_gt_i32_e32 vcc, 1, v27
	v_lshrrev_b32_e32 v25, 16, v25
	s_nop 0
	v_cndmask_b32_e32 v26, v28, v26, vcc
	v_and_b32_e32 v28, 7, v26
	v_cmp_lt_i32_e32 vcc, 5, v28
	v_lshrrev_b32_e32 v26, 2, v26
	s_nop 0
	v_cndmask_b32_e64 v29, 0, 1, vcc
	v_cmp_eq_u32_e32 vcc, 3, v28
	s_nop 1
	v_cndmask_b32_e64 v28, 0, 1, vcc
	v_or_b32_e32 v28, v28, v29
	v_add_u32_e32 v26, v26, v28
	v_cmp_gt_i32_e32 vcc, 31, v27
	s_nop 1
	v_cndmask_b32_e32 v26, v22, v26, vcc
	v_cmp_ne_u32_e32 vcc, 0, v24
	s_nop 1
	v_cndmask_b32_e32 v24, v22, v23, vcc
	v_cmp_eq_u32_e32 vcc, s93, v27
	s_nop 1
	v_cndmask_b32_e32 v24, v26, v24, vcc
	v_and_or_b32 v24, v25, s70, v24
	v_perm_b32 v7, v24, v7, s71
	global_store_dword v[16:17], v7, off offset:1024
	v_cvt_f64_f32_e32 v[24:25], v125
	v_cvt_f64_f32_e32 v[26:27], v141
	v_mul_f64 v[28:29], v[18:19], v[26:27]
	v_fma_f64 v[28:29], v[12:13], v[24:25], -v[28:29]
	v_mul_f64 v[26:27], v[12:13], v[26:27]
	v_fmac_f64_e32 v[26:27], v[18:19], v[24:25]
	v_ldexp_f64 v[24:25], v[28:29], 10
	v_and_or_b32 v7, v25, s33, v24
	v_cmp_ne_u32_e32 vcc, 0, v7
	v_lshrrev_b32_e32 v24, 8, v25
	v_bfe_u32 v28, v25, 20, 11
	v_cndmask_b32_e64 v7, 0, 1, vcc
	v_and_or_b32 v7, v24, s92, v7
	v_sub_u32_e32 v29, 0x3f1, v28
	v_or_b32_e32 v24, 0x1000, v7
	v_med3_i32 v29, v29, 0, 13
	v_lshrrev_b32_e32 v30, v29, v24
	v_lshlrev_b32_e32 v29, v29, v30
	v_cmp_ne_u32_e32 vcc, v29, v24
	v_add_u32_e32 v28, 0xfffffc10, v28
	v_lshl_or_b32 v29, v28, 12, v7
	v_cndmask_b32_e64 v24, 0, 1, vcc
	v_or_b32_e32 v24, v30, v24
	v_cmp_gt_i32_e32 vcc, 1, v28
	s_nop 1
	v_cndmask_b32_e32 v24, v29, v24, vcc
	v_and_b32_e32 v29, 7, v24
	v_cmp_lt_i32_e32 vcc, 5, v29
	v_lshrrev_b32_e32 v24, 2, v24
	s_nop 0
	v_cndmask_b32_e64 v30, 0, 1, vcc
	v_cmp_eq_u32_e32 vcc, 3, v29
	s_nop 1
	v_cndmask_b32_e64 v29, 0, 1, vcc
	v_or_b32_e32 v29, v29, v30
	v_add_u32_e32 v24, v24, v29
	v_cmp_gt_i32_e32 vcc, 31, v28
	s_nop 1
	v_cndmask_b32_e32 v24, v22, v24, vcc
	v_cmp_ne_u32_e32 vcc, 0, v7
	s_nop 1
	v_cndmask_b32_e32 v7, v22, v23, vcc
	v_cmp_eq_u32_e32 vcc, s93, v28
	s_nop 1
	v_cndmask_b32_e32 v7, v24, v7, vcc
	v_lshrrev_b32_e32 v24, 16, v25
	v_and_or_b32 v7, v24, s70, v7
	v_ldexp_f64 v[24:25], -v[26:27], 10
	v_and_or_b32 v24, v25, s33, v24
	v_cmp_ne_u32_e32 vcc, 0, v24
	v_lshrrev_b32_e32 v26, 8, v25
	v_bfe_u32 v27, v25, 20, 11
	v_cndmask_b32_e64 v24, 0, 1, vcc
	v_and_or_b32 v24, v26, s92, v24
	v_sub_u32_e32 v28, 0x3f1, v27
	v_or_b32_e32 v26, 0x1000, v24
	v_med3_i32 v28, v28, 0, 13
	v_lshrrev_b32_e32 v29, v28, v26
	v_lshlrev_b32_e32 v28, v28, v29
	v_cmp_ne_u32_e32 vcc, v28, v26
	v_add_u32_e32 v27, 0xfffffc10, v27
	v_lshl_or_b32 v28, v27, 12, v24
	v_cndmask_b32_e64 v26, 0, 1, vcc
	v_or_b32_e32 v26, v29, v26
	v_cmp_gt_i32_e32 vcc, 1, v27
	v_lshrrev_b32_e32 v25, 16, v25
	s_nop 0
	v_cndmask_b32_e32 v26, v28, v26, vcc
	v_and_b32_e32 v28, 7, v26
	v_cmp_lt_i32_e32 vcc, 5, v28
	v_lshrrev_b32_e32 v26, 2, v26
	s_nop 0
	v_cndmask_b32_e64 v29, 0, 1, vcc
	v_cmp_eq_u32_e32 vcc, 3, v28
	s_nop 1
	v_cndmask_b32_e64 v28, 0, 1, vcc
	v_or_b32_e32 v28, v28, v29
	v_add_u32_e32 v26, v26, v28
	v_cmp_gt_i32_e32 vcc, 31, v27
	s_nop 1
	v_cndmask_b32_e32 v26, v22, v26, vcc
	v_cmp_ne_u32_e32 vcc, 0, v24
	s_nop 1
	v_cndmask_b32_e32 v24, v22, v23, vcc
	v_cmp_eq_u32_e32 vcc, s93, v27
	s_nop 1
	v_cndmask_b32_e32 v24, v26, v24, vcc
	v_and_or_b32 v24, v25, s70, v24
	v_perm_b32 v7, v24, v7, s71
	global_store_dword v[16:17], v7, off offset:1280
	v_cvt_f64_f32_e32 v[24:25], v126
	v_cvt_f64_f32_e32 v[26:27], v142
	v_mul_f64 v[28:29], v[18:19], v[26:27]
	v_fma_f64 v[28:29], v[12:13], v[24:25], -v[28:29]
	v_mul_f64 v[26:27], v[12:13], v[26:27]
	v_fmac_f64_e32 v[26:27], v[18:19], v[24:25]
	v_ldexp_f64 v[24:25], v[28:29], 10
	v_and_or_b32 v7, v25, s33, v24
	v_cmp_ne_u32_e32 vcc, 0, v7
	v_lshrrev_b32_e32 v24, 8, v25
	v_bfe_u32 v28, v25, 20, 11
	v_cndmask_b32_e64 v7, 0, 1, vcc
	v_and_or_b32 v7, v24, s92, v7
	v_sub_u32_e32 v29, 0x3f1, v28
	v_or_b32_e32 v24, 0x1000, v7
	v_med3_i32 v29, v29, 0, 13
	v_lshrrev_b32_e32 v30, v29, v24
	v_lshlrev_b32_e32 v29, v29, v30
	v_cmp_ne_u32_e32 vcc, v29, v24
	v_add_u32_e32 v28, 0xfffffc10, v28
	v_lshl_or_b32 v29, v28, 12, v7
	v_cndmask_b32_e64 v24, 0, 1, vcc
	v_or_b32_e32 v24, v30, v24
	v_cmp_gt_i32_e32 vcc, 1, v28
	s_nop 1
	v_cndmask_b32_e32 v24, v29, v24, vcc
	v_and_b32_e32 v29, 7, v24
	v_cmp_lt_i32_e32 vcc, 5, v29
	v_lshrrev_b32_e32 v24, 2, v24
	s_nop 0
	v_cndmask_b32_e64 v30, 0, 1, vcc
	v_cmp_eq_u32_e32 vcc, 3, v29
	s_nop 1
	v_cndmask_b32_e64 v29, 0, 1, vcc
	v_or_b32_e32 v29, v29, v30
	v_add_u32_e32 v24, v24, v29
	v_cmp_gt_i32_e32 vcc, 31, v28
	s_nop 1
	v_cndmask_b32_e32 v24, v22, v24, vcc
	v_cmp_ne_u32_e32 vcc, 0, v7
	s_nop 1
	v_cndmask_b32_e32 v7, v22, v23, vcc
	v_cmp_eq_u32_e32 vcc, s93, v28
	s_nop 1
	v_cndmask_b32_e32 v7, v24, v7, vcc
	v_lshrrev_b32_e32 v24, 16, v25
	v_and_or_b32 v7, v24, s70, v7
	v_ldexp_f64 v[24:25], -v[26:27], 10
	v_and_or_b32 v24, v25, s33, v24
	v_cmp_ne_u32_e32 vcc, 0, v24
	v_lshrrev_b32_e32 v26, 8, v25
	v_bfe_u32 v27, v25, 20, 11
	v_cndmask_b32_e64 v24, 0, 1, vcc
	v_and_or_b32 v24, v26, s92, v24
	v_sub_u32_e32 v28, 0x3f1, v27
	v_or_b32_e32 v26, 0x1000, v24
	v_med3_i32 v28, v28, 0, 13
	v_lshrrev_b32_e32 v29, v28, v26
	v_lshlrev_b32_e32 v28, v28, v29
	v_cmp_ne_u32_e32 vcc, v28, v26
	v_add_u32_e32 v27, 0xfffffc10, v27
	v_lshl_or_b32 v28, v27, 12, v24
	v_cndmask_b32_e64 v26, 0, 1, vcc
	v_or_b32_e32 v26, v29, v26
	v_cmp_gt_i32_e32 vcc, 1, v27
	v_lshrrev_b32_e32 v25, 16, v25
	s_nop 0
	v_cndmask_b32_e32 v26, v28, v26, vcc
	v_and_b32_e32 v28, 7, v26
	v_cmp_lt_i32_e32 vcc, 5, v28
	v_lshrrev_b32_e32 v26, 2, v26
	s_nop 0
	v_cndmask_b32_e64 v29, 0, 1, vcc
	v_cmp_eq_u32_e32 vcc, 3, v28
	s_nop 1
	v_cndmask_b32_e64 v28, 0, 1, vcc
	v_or_b32_e32 v28, v28, v29
	v_add_u32_e32 v26, v26, v28
	v_cmp_gt_i32_e32 vcc, 31, v27
	s_nop 1
	v_cndmask_b32_e32 v26, v22, v26, vcc
	v_cmp_ne_u32_e32 vcc, 0, v24
	s_nop 1
	v_cndmask_b32_e32 v24, v22, v23, vcc
	v_cmp_eq_u32_e32 vcc, s93, v27
	s_nop 1
	v_cndmask_b32_e32 v24, v26, v24, vcc
	v_and_or_b32 v24, v25, s70, v24
	v_perm_b32 v7, v24, v7, s71
	global_store_dword v[16:17], v7, off offset:1536
	v_cvt_f64_f32_e32 v[24:25], v127
	v_cvt_f64_f32_e32 v[26:27], v143
	v_mul_f64 v[28:29], v[18:19], v[26:27]
	v_fma_f64 v[28:29], v[12:13], v[24:25], -v[28:29]
	v_mul_f64 v[26:27], v[12:13], v[26:27]
	v_fmac_f64_e32 v[26:27], v[18:19], v[24:25]
	v_ldexp_f64 v[24:25], v[28:29], 10
	v_and_or_b32 v7, v25, s33, v24
	v_cmp_ne_u32_e32 vcc, 0, v7
	v_lshrrev_b32_e32 v24, 8, v25
	v_bfe_u32 v28, v25, 20, 11
	v_cndmask_b32_e64 v7, 0, 1, vcc
	v_and_or_b32 v7, v24, s92, v7
	v_sub_u32_e32 v29, 0x3f1, v28
	v_or_b32_e32 v24, 0x1000, v7
	v_med3_i32 v29, v29, 0, 13
	v_lshrrev_b32_e32 v30, v29, v24
	v_lshlrev_b32_e32 v29, v29, v30
	v_cmp_ne_u32_e32 vcc, v29, v24
	v_add_u32_e32 v28, 0xfffffc10, v28
	v_lshl_or_b32 v29, v28, 12, v7
	v_cndmask_b32_e64 v24, 0, 1, vcc
	v_or_b32_e32 v24, v30, v24
	v_cmp_gt_i32_e32 vcc, 1, v28
	s_nop 1
	v_cndmask_b32_e32 v24, v29, v24, vcc
	v_and_b32_e32 v29, 7, v24
	v_cmp_lt_i32_e32 vcc, 5, v29
	v_lshrrev_b32_e32 v24, 2, v24
	s_nop 0
	v_cndmask_b32_e64 v30, 0, 1, vcc
	v_cmp_eq_u32_e32 vcc, 3, v29
	s_nop 1
	v_cndmask_b32_e64 v29, 0, 1, vcc
	v_or_b32_e32 v29, v29, v30
	v_add_u32_e32 v24, v24, v29
	v_cmp_gt_i32_e32 vcc, 31, v28
	s_nop 1
	v_cndmask_b32_e32 v24, v22, v24, vcc
	v_cmp_ne_u32_e32 vcc, 0, v7
	s_nop 1
	v_cndmask_b32_e32 v7, v22, v23, vcc
	v_cmp_eq_u32_e32 vcc, s93, v28
	s_nop 1
	v_cndmask_b32_e32 v7, v24, v7, vcc
	v_lshrrev_b32_e32 v24, 16, v25
	v_and_or_b32 v7, v24, s70, v7
	v_ldexp_f64 v[24:25], -v[26:27], 10
	v_and_or_b32 v24, v25, s33, v24
	v_cmp_ne_u32_e32 vcc, 0, v24
	v_lshrrev_b32_e32 v26, 8, v25
	v_bfe_u32 v27, v25, 20, 11
	v_cndmask_b32_e64 v24, 0, 1, vcc
	v_and_or_b32 v24, v26, s92, v24
	v_sub_u32_e32 v28, 0x3f1, v27
	v_or_b32_e32 v26, 0x1000, v24
	v_med3_i32 v28, v28, 0, 13
	v_lshrrev_b32_e32 v29, v28, v26
	v_lshlrev_b32_e32 v28, v28, v29
	v_cmp_ne_u32_e32 vcc, v28, v26
	v_add_u32_e32 v27, 0xfffffc10, v27
	v_lshl_or_b32 v28, v27, 12, v24
	v_cndmask_b32_e64 v26, 0, 1, vcc
	v_or_b32_e32 v26, v29, v26
	v_cmp_gt_i32_e32 vcc, 1, v27
	v_lshrrev_b32_e32 v25, 16, v25
	s_nop 0
	v_cndmask_b32_e32 v26, v28, v26, vcc
	v_and_b32_e32 v28, 7, v26
	v_cmp_lt_i32_e32 vcc, 5, v28
	v_lshrrev_b32_e32 v26, 2, v26
	s_nop 0
	v_cndmask_b32_e64 v29, 0, 1, vcc
	v_cmp_eq_u32_e32 vcc, 3, v28
	s_nop 1
	v_cndmask_b32_e64 v28, 0, 1, vcc
	v_or_b32_e32 v28, v28, v29
	v_add_u32_e32 v26, v26, v28
	v_cmp_gt_i32_e32 vcc, 31, v27
	s_nop 1
	v_cndmask_b32_e32 v26, v22, v26, vcc
	v_cmp_ne_u32_e32 vcc, 0, v24
	s_nop 1
	v_cndmask_b32_e32 v24, v22, v23, vcc
	v_cmp_eq_u32_e32 vcc, s93, v27
	s_nop 1
	v_cndmask_b32_e32 v24, v26, v24, vcc
	v_and_or_b32 v24, v25, s70, v24
	v_perm_b32 v7, v24, v7, s71
	global_store_dword v[16:17], v7, off offset:1792
	v_cvt_f64_f32_e32 v[24:25], v128
	v_cvt_f64_f32_e32 v[26:27], v144
	v_mul_f64 v[28:29], v[18:19], v[26:27]
	v_fma_f64 v[28:29], v[12:13], v[24:25], -v[28:29]
	v_mul_f64 v[26:27], v[12:13], v[26:27]
	v_fmac_f64_e32 v[26:27], v[18:19], v[24:25]
	v_ldexp_f64 v[24:25], v[28:29], 10
	v_and_or_b32 v7, v25, s33, v24
	v_cmp_ne_u32_e32 vcc, 0, v7
	v_lshrrev_b32_e32 v24, 8, v25
	v_bfe_u32 v28, v25, 20, 11
	v_cndmask_b32_e64 v7, 0, 1, vcc
	v_and_or_b32 v7, v24, s92, v7
	v_sub_u32_e32 v29, 0x3f1, v28
	v_or_b32_e32 v24, 0x1000, v7
	v_med3_i32 v29, v29, 0, 13
	v_lshrrev_b32_e32 v30, v29, v24
	v_lshlrev_b32_e32 v29, v29, v30
	v_cmp_ne_u32_e32 vcc, v29, v24
	v_add_u32_e32 v28, 0xfffffc10, v28
	v_lshl_or_b32 v29, v28, 12, v7
	v_cndmask_b32_e64 v24, 0, 1, vcc
	v_or_b32_e32 v24, v30, v24
	v_cmp_gt_i32_e32 vcc, 1, v28
	s_nop 1
	v_cndmask_b32_e32 v24, v29, v24, vcc
	v_and_b32_e32 v29, 7, v24
	v_cmp_lt_i32_e32 vcc, 5, v29
	v_lshrrev_b32_e32 v24, 2, v24
	s_nop 0
	v_cndmask_b32_e64 v30, 0, 1, vcc
	v_cmp_eq_u32_e32 vcc, 3, v29
	s_nop 1
	v_cndmask_b32_e64 v29, 0, 1, vcc
	v_or_b32_e32 v29, v29, v30
	v_add_u32_e32 v24, v24, v29
	v_cmp_gt_i32_e32 vcc, 31, v28
	s_nop 1
	v_cndmask_b32_e32 v24, v22, v24, vcc
	v_cmp_ne_u32_e32 vcc, 0, v7
	s_nop 1
	v_cndmask_b32_e32 v7, v22, v23, vcc
	v_cmp_eq_u32_e32 vcc, s93, v28
	s_nop 1
	v_cndmask_b32_e32 v7, v24, v7, vcc
	v_lshrrev_b32_e32 v24, 16, v25
	v_and_or_b32 v7, v24, s70, v7
	v_ldexp_f64 v[24:25], -v[26:27], 10
	v_and_or_b32 v24, v25, s33, v24
	v_cmp_ne_u32_e32 vcc, 0, v24
	v_lshrrev_b32_e32 v26, 8, v25
	v_bfe_u32 v27, v25, 20, 11
	v_cndmask_b32_e64 v24, 0, 1, vcc
	v_and_or_b32 v24, v26, s92, v24
	v_sub_u32_e32 v28, 0x3f1, v27
	v_or_b32_e32 v26, 0x1000, v24
	v_med3_i32 v28, v28, 0, 13
	v_lshrrev_b32_e32 v29, v28, v26
	v_lshlrev_b32_e32 v28, v28, v29
	v_cmp_ne_u32_e32 vcc, v28, v26
	v_add_u32_e32 v27, 0xfffffc10, v27
	v_lshl_or_b32 v28, v27, 12, v24
	v_cndmask_b32_e64 v26, 0, 1, vcc
	v_or_b32_e32 v26, v29, v26
	v_cmp_gt_i32_e32 vcc, 1, v27
	v_lshrrev_b32_e32 v25, 16, v25
	s_nop 0
	v_cndmask_b32_e32 v26, v28, v26, vcc
	v_and_b32_e32 v28, 7, v26
	v_cmp_lt_i32_e32 vcc, 5, v28
	v_lshrrev_b32_e32 v26, 2, v26
	s_nop 0
	v_cndmask_b32_e64 v29, 0, 1, vcc
	v_cmp_eq_u32_e32 vcc, 3, v28
	s_nop 1
	v_cndmask_b32_e64 v28, 0, 1, vcc
	v_or_b32_e32 v28, v28, v29
	v_add_u32_e32 v26, v26, v28
	v_cmp_gt_i32_e32 vcc, 31, v27
	s_nop 1
	v_cndmask_b32_e32 v26, v22, v26, vcc
	v_cmp_ne_u32_e32 vcc, 0, v24
	s_nop 1
	v_cndmask_b32_e32 v24, v22, v23, vcc
	v_cmp_eq_u32_e32 vcc, s93, v27
	s_nop 1
	v_cndmask_b32_e32 v24, v26, v24, vcc
	v_and_or_b32 v24, v25, s70, v24
	v_perm_b32 v7, v24, v7, s71
	global_store_dword v[16:17], v7, off offset:2048
	v_cvt_f64_f32_e32 v[24:25], v129
	v_cvt_f64_f32_e32 v[26:27], v145
	v_mul_f64 v[28:29], v[18:19], v[26:27]
	v_fma_f64 v[28:29], v[12:13], v[24:25], -v[28:29]
	v_mul_f64 v[26:27], v[12:13], v[26:27]
	v_fmac_f64_e32 v[26:27], v[18:19], v[24:25]
	v_ldexp_f64 v[24:25], v[28:29], 10
	v_and_or_b32 v7, v25, s33, v24
	v_cmp_ne_u32_e32 vcc, 0, v7
	v_lshrrev_b32_e32 v24, 8, v25
	v_bfe_u32 v28, v25, 20, 11
	v_cndmask_b32_e64 v7, 0, 1, vcc
	v_and_or_b32 v7, v24, s92, v7
	v_sub_u32_e32 v29, 0x3f1, v28
	v_or_b32_e32 v24, 0x1000, v7
	v_med3_i32 v29, v29, 0, 13
	v_lshrrev_b32_e32 v30, v29, v24
	v_lshlrev_b32_e32 v29, v29, v30
	v_cmp_ne_u32_e32 vcc, v29, v24
	v_add_u32_e32 v28, 0xfffffc10, v28
	v_lshl_or_b32 v29, v28, 12, v7
	v_cndmask_b32_e64 v24, 0, 1, vcc
	v_or_b32_e32 v24, v30, v24
	v_cmp_gt_i32_e32 vcc, 1, v28
	s_nop 1
	v_cndmask_b32_e32 v24, v29, v24, vcc
	v_and_b32_e32 v29, 7, v24
	v_cmp_lt_i32_e32 vcc, 5, v29
	v_lshrrev_b32_e32 v24, 2, v24
	s_nop 0
	v_cndmask_b32_e64 v30, 0, 1, vcc
	v_cmp_eq_u32_e32 vcc, 3, v29
	s_nop 1
	v_cndmask_b32_e64 v29, 0, 1, vcc
	v_or_b32_e32 v29, v29, v30
	v_add_u32_e32 v24, v24, v29
	v_cmp_gt_i32_e32 vcc, 31, v28
	s_nop 1
	v_cndmask_b32_e32 v24, v22, v24, vcc
	v_cmp_ne_u32_e32 vcc, 0, v7
	s_nop 1
	v_cndmask_b32_e32 v7, v22, v23, vcc
	v_cmp_eq_u32_e32 vcc, s93, v28
	s_nop 1
	v_cndmask_b32_e32 v7, v24, v7, vcc
	v_lshrrev_b32_e32 v24, 16, v25
	v_and_or_b32 v7, v24, s70, v7
	v_ldexp_f64 v[24:25], -v[26:27], 10
	v_and_or_b32 v24, v25, s33, v24
	v_cmp_ne_u32_e32 vcc, 0, v24
	v_lshrrev_b32_e32 v26, 8, v25
	v_bfe_u32 v27, v25, 20, 11
	v_cndmask_b32_e64 v24, 0, 1, vcc
	v_and_or_b32 v24, v26, s92, v24
	v_sub_u32_e32 v28, 0x3f1, v27
	v_or_b32_e32 v26, 0x1000, v24
	v_med3_i32 v28, v28, 0, 13
	v_lshrrev_b32_e32 v29, v28, v26
	v_lshlrev_b32_e32 v28, v28, v29
	v_cmp_ne_u32_e32 vcc, v28, v26
	v_add_u32_e32 v27, 0xfffffc10, v27
	v_lshl_or_b32 v28, v27, 12, v24
	v_cndmask_b32_e64 v26, 0, 1, vcc
	v_or_b32_e32 v26, v29, v26
	v_cmp_gt_i32_e32 vcc, 1, v27
	v_lshrrev_b32_e32 v25, 16, v25
	s_nop 0
	v_cndmask_b32_e32 v26, v28, v26, vcc
	v_and_b32_e32 v28, 7, v26
	v_cmp_lt_i32_e32 vcc, 5, v28
	v_lshrrev_b32_e32 v26, 2, v26
	s_nop 0
	v_cndmask_b32_e64 v29, 0, 1, vcc
	v_cmp_eq_u32_e32 vcc, 3, v28
	s_nop 1
	v_cndmask_b32_e64 v28, 0, 1, vcc
	v_or_b32_e32 v28, v28, v29
	v_add_u32_e32 v26, v26, v28
	v_cmp_gt_i32_e32 vcc, 31, v27
	s_nop 1
	v_cndmask_b32_e32 v26, v22, v26, vcc
	v_cmp_ne_u32_e32 vcc, 0, v24
	s_nop 1
	v_cndmask_b32_e32 v24, v22, v23, vcc
	v_cmp_eq_u32_e32 vcc, s93, v27
	s_nop 1
	v_cndmask_b32_e32 v24, v26, v24, vcc
	v_and_or_b32 v24, v25, s70, v24
	v_perm_b32 v7, v24, v7, s71
	global_store_dword v[16:17], v7, off offset:2304
	v_cvt_f64_f32_e32 v[24:25], v130
	v_cvt_f64_f32_e32 v[26:27], v146
	v_mul_f64 v[28:29], v[18:19], v[26:27]
	v_fma_f64 v[28:29], v[12:13], v[24:25], -v[28:29]
	v_mul_f64 v[26:27], v[12:13], v[26:27]
	v_fmac_f64_e32 v[26:27], v[18:19], v[24:25]
	v_ldexp_f64 v[24:25], v[28:29], 10
	v_and_or_b32 v7, v25, s33, v24
	v_cmp_ne_u32_e32 vcc, 0, v7
	v_lshrrev_b32_e32 v24, 8, v25
	v_bfe_u32 v28, v25, 20, 11
	v_cndmask_b32_e64 v7, 0, 1, vcc
	v_and_or_b32 v7, v24, s92, v7
	v_sub_u32_e32 v29, 0x3f1, v28
	v_or_b32_e32 v24, 0x1000, v7
	v_med3_i32 v29, v29, 0, 13
	v_lshrrev_b32_e32 v30, v29, v24
	v_lshlrev_b32_e32 v29, v29, v30
	v_cmp_ne_u32_e32 vcc, v29, v24
	v_add_u32_e32 v28, 0xfffffc10, v28
	v_lshl_or_b32 v29, v28, 12, v7
	v_cndmask_b32_e64 v24, 0, 1, vcc
	v_or_b32_e32 v24, v30, v24
	v_cmp_gt_i32_e32 vcc, 1, v28
	s_nop 1
	v_cndmask_b32_e32 v24, v29, v24, vcc
	v_and_b32_e32 v29, 7, v24
	v_cmp_lt_i32_e32 vcc, 5, v29
	v_lshrrev_b32_e32 v24, 2, v24
	s_nop 0
	v_cndmask_b32_e64 v30, 0, 1, vcc
	v_cmp_eq_u32_e32 vcc, 3, v29
	s_nop 1
	v_cndmask_b32_e64 v29, 0, 1, vcc
	v_or_b32_e32 v29, v29, v30
	v_add_u32_e32 v24, v24, v29
	v_cmp_gt_i32_e32 vcc, 31, v28
	s_nop 1
	v_cndmask_b32_e32 v24, v22, v24, vcc
	v_cmp_ne_u32_e32 vcc, 0, v7
	s_nop 1
	v_cndmask_b32_e32 v7, v22, v23, vcc
	v_cmp_eq_u32_e32 vcc, s93, v28
	s_nop 1
	v_cndmask_b32_e32 v7, v24, v7, vcc
	v_lshrrev_b32_e32 v24, 16, v25
	v_and_or_b32 v7, v24, s70, v7
	v_ldexp_f64 v[24:25], -v[26:27], 10
	v_and_or_b32 v24, v25, s33, v24
	v_cmp_ne_u32_e32 vcc, 0, v24
	v_lshrrev_b32_e32 v26, 8, v25
	v_bfe_u32 v27, v25, 20, 11
	v_cndmask_b32_e64 v24, 0, 1, vcc
	v_and_or_b32 v24, v26, s92, v24
	v_sub_u32_e32 v28, 0x3f1, v27
	v_or_b32_e32 v26, 0x1000, v24
	v_med3_i32 v28, v28, 0, 13
	v_lshrrev_b32_e32 v29, v28, v26
	v_lshlrev_b32_e32 v28, v28, v29
	v_cmp_ne_u32_e32 vcc, v28, v26
	v_add_u32_e32 v27, 0xfffffc10, v27
	v_lshl_or_b32 v28, v27, 12, v24
	v_cndmask_b32_e64 v26, 0, 1, vcc
	v_or_b32_e32 v26, v29, v26
	v_cmp_gt_i32_e32 vcc, 1, v27
	v_lshrrev_b32_e32 v25, 16, v25
	s_nop 0
	v_cndmask_b32_e32 v26, v28, v26, vcc
	v_and_b32_e32 v28, 7, v26
	v_cmp_lt_i32_e32 vcc, 5, v28
	v_lshrrev_b32_e32 v26, 2, v26
	s_nop 0
	v_cndmask_b32_e64 v29, 0, 1, vcc
	v_cmp_eq_u32_e32 vcc, 3, v28
	s_nop 1
	v_cndmask_b32_e64 v28, 0, 1, vcc
	v_or_b32_e32 v28, v28, v29
	v_add_u32_e32 v26, v26, v28
	v_cmp_gt_i32_e32 vcc, 31, v27
	s_nop 1
	v_cndmask_b32_e32 v26, v22, v26, vcc
	v_cmp_ne_u32_e32 vcc, 0, v24
	s_nop 1
	v_cndmask_b32_e32 v24, v22, v23, vcc
	v_cmp_eq_u32_e32 vcc, s93, v27
	s_nop 1
	v_cndmask_b32_e32 v24, v26, v24, vcc
	v_and_or_b32 v24, v25, s70, v24
	v_perm_b32 v7, v24, v7, s71
	global_store_dword v[16:17], v7, off offset:2560
	v_cvt_f64_f32_e32 v[24:25], v131
	v_cvt_f64_f32_e32 v[26:27], v147
	v_mul_f64 v[28:29], v[18:19], v[26:27]
	v_fma_f64 v[28:29], v[12:13], v[24:25], -v[28:29]
	v_mul_f64 v[26:27], v[12:13], v[26:27]
	v_fmac_f64_e32 v[26:27], v[18:19], v[24:25]
	v_ldexp_f64 v[24:25], v[28:29], 10
	v_and_or_b32 v7, v25, s33, v24
	v_cmp_ne_u32_e32 vcc, 0, v7
	v_lshrrev_b32_e32 v24, 8, v25
	v_bfe_u32 v28, v25, 20, 11
	v_cndmask_b32_e64 v7, 0, 1, vcc
	v_and_or_b32 v7, v24, s92, v7
	v_sub_u32_e32 v29, 0x3f1, v28
	v_or_b32_e32 v24, 0x1000, v7
	v_med3_i32 v29, v29, 0, 13
	v_lshrrev_b32_e32 v30, v29, v24
	v_lshlrev_b32_e32 v29, v29, v30
	v_cmp_ne_u32_e32 vcc, v29, v24
	v_add_u32_e32 v28, 0xfffffc10, v28
	v_lshl_or_b32 v29, v28, 12, v7
	v_cndmask_b32_e64 v24, 0, 1, vcc
	v_or_b32_e32 v24, v30, v24
	v_cmp_gt_i32_e32 vcc, 1, v28
	s_nop 1
	v_cndmask_b32_e32 v24, v29, v24, vcc
	v_and_b32_e32 v29, 7, v24
	v_cmp_lt_i32_e32 vcc, 5, v29
	v_lshrrev_b32_e32 v24, 2, v24
	s_nop 0
	v_cndmask_b32_e64 v30, 0, 1, vcc
	v_cmp_eq_u32_e32 vcc, 3, v29
	s_nop 1
	v_cndmask_b32_e64 v29, 0, 1, vcc
	v_or_b32_e32 v29, v29, v30
	v_add_u32_e32 v24, v24, v29
	v_cmp_gt_i32_e32 vcc, 31, v28
	s_nop 1
	v_cndmask_b32_e32 v24, v22, v24, vcc
	v_cmp_ne_u32_e32 vcc, 0, v7
	s_nop 1
	v_cndmask_b32_e32 v7, v22, v23, vcc
	v_cmp_eq_u32_e32 vcc, s93, v28
	s_nop 1
	v_cndmask_b32_e32 v7, v24, v7, vcc
	v_lshrrev_b32_e32 v24, 16, v25
	v_and_or_b32 v7, v24, s70, v7
	v_ldexp_f64 v[24:25], -v[26:27], 10
	v_and_or_b32 v24, v25, s33, v24
	v_cmp_ne_u32_e32 vcc, 0, v24
	v_lshrrev_b32_e32 v26, 8, v25
	v_bfe_u32 v27, v25, 20, 11
	v_cndmask_b32_e64 v24, 0, 1, vcc
	v_and_or_b32 v24, v26, s92, v24
	v_sub_u32_e32 v28, 0x3f1, v27
	v_or_b32_e32 v26, 0x1000, v24
	v_med3_i32 v28, v28, 0, 13
	v_lshrrev_b32_e32 v29, v28, v26
	v_lshlrev_b32_e32 v28, v28, v29
	v_cmp_ne_u32_e32 vcc, v28, v26
	v_add_u32_e32 v27, 0xfffffc10, v27
	v_lshl_or_b32 v28, v27, 12, v24
	v_cndmask_b32_e64 v26, 0, 1, vcc
	v_or_b32_e32 v26, v29, v26
	v_cmp_gt_i32_e32 vcc, 1, v27
	v_lshrrev_b32_e32 v25, 16, v25
	s_nop 0
	v_cndmask_b32_e32 v26, v28, v26, vcc
	v_and_b32_e32 v28, 7, v26
	v_cmp_lt_i32_e32 vcc, 5, v28
	v_lshrrev_b32_e32 v26, 2, v26
	s_nop 0
	v_cndmask_b32_e64 v29, 0, 1, vcc
	v_cmp_eq_u32_e32 vcc, 3, v28
	s_nop 1
	v_cndmask_b32_e64 v28, 0, 1, vcc
	v_or_b32_e32 v28, v28, v29
	v_add_u32_e32 v26, v26, v28
	v_cmp_gt_i32_e32 vcc, 31, v27
	s_nop 1
	v_cndmask_b32_e32 v26, v22, v26, vcc
	v_cmp_ne_u32_e32 vcc, 0, v24
	s_nop 1
	v_cndmask_b32_e32 v24, v22, v23, vcc
	v_cmp_eq_u32_e32 vcc, s93, v27
	s_nop 1
	v_cndmask_b32_e32 v24, v26, v24, vcc
	v_and_or_b32 v24, v25, s70, v24
	v_perm_b32 v7, v24, v7, s71
	global_store_dword v[16:17], v7, off offset:2816
	v_cvt_f64_f32_e32 v[24:25], v132
	v_cvt_f64_f32_e32 v[26:27], v148
	v_mul_f64 v[28:29], v[18:19], v[26:27]
	v_fma_f64 v[28:29], v[12:13], v[24:25], -v[28:29]
	v_mul_f64 v[26:27], v[12:13], v[26:27]
	v_fmac_f64_e32 v[26:27], v[18:19], v[24:25]
	v_ldexp_f64 v[24:25], v[28:29], 10
	v_and_or_b32 v7, v25, s33, v24
	v_cmp_ne_u32_e32 vcc, 0, v7
	v_lshrrev_b32_e32 v24, 8, v25
	v_bfe_u32 v28, v25, 20, 11
	v_cndmask_b32_e64 v7, 0, 1, vcc
	v_and_or_b32 v7, v24, s92, v7
	v_sub_u32_e32 v29, 0x3f1, v28
	v_or_b32_e32 v24, 0x1000, v7
	v_med3_i32 v29, v29, 0, 13
	v_lshrrev_b32_e32 v30, v29, v24
	v_lshlrev_b32_e32 v29, v29, v30
	v_cmp_ne_u32_e32 vcc, v29, v24
	v_add_u32_e32 v28, 0xfffffc10, v28
	v_lshl_or_b32 v29, v28, 12, v7
	v_cndmask_b32_e64 v24, 0, 1, vcc
	v_or_b32_e32 v24, v30, v24
	v_cmp_gt_i32_e32 vcc, 1, v28
	s_nop 1
	v_cndmask_b32_e32 v24, v29, v24, vcc
	v_and_b32_e32 v29, 7, v24
	v_cmp_lt_i32_e32 vcc, 5, v29
	v_lshrrev_b32_e32 v24, 2, v24
	s_nop 0
	v_cndmask_b32_e64 v30, 0, 1, vcc
	v_cmp_eq_u32_e32 vcc, 3, v29
	s_nop 1
	v_cndmask_b32_e64 v29, 0, 1, vcc
	v_or_b32_e32 v29, v29, v30
	v_add_u32_e32 v24, v24, v29
	v_cmp_gt_i32_e32 vcc, 31, v28
	s_nop 1
	v_cndmask_b32_e32 v24, v22, v24, vcc
	v_cmp_ne_u32_e32 vcc, 0, v7
	s_nop 1
	v_cndmask_b32_e32 v7, v22, v23, vcc
	v_cmp_eq_u32_e32 vcc, s93, v28
	s_nop 1
	v_cndmask_b32_e32 v7, v24, v7, vcc
	v_lshrrev_b32_e32 v24, 16, v25
	v_and_or_b32 v7, v24, s70, v7
	v_ldexp_f64 v[24:25], -v[26:27], 10
	v_and_or_b32 v24, v25, s33, v24
	v_cmp_ne_u32_e32 vcc, 0, v24
	v_lshrrev_b32_e32 v26, 8, v25
	v_bfe_u32 v27, v25, 20, 11
	v_cndmask_b32_e64 v24, 0, 1, vcc
	v_and_or_b32 v24, v26, s92, v24
	v_sub_u32_e32 v28, 0x3f1, v27
	v_or_b32_e32 v26, 0x1000, v24
	v_med3_i32 v28, v28, 0, 13
	v_lshrrev_b32_e32 v29, v28, v26
	v_lshlrev_b32_e32 v28, v28, v29
	v_cmp_ne_u32_e32 vcc, v28, v26
	v_add_u32_e32 v27, 0xfffffc10, v27
	v_lshl_or_b32 v28, v27, 12, v24
	v_cndmask_b32_e64 v26, 0, 1, vcc
	v_or_b32_e32 v26, v29, v26
	v_cmp_gt_i32_e32 vcc, 1, v27
	v_lshrrev_b32_e32 v25, 16, v25
	s_nop 0
	v_cndmask_b32_e32 v26, v28, v26, vcc
	v_and_b32_e32 v28, 7, v26
	v_cmp_lt_i32_e32 vcc, 5, v28
	v_lshrrev_b32_e32 v26, 2, v26
	s_nop 0
	v_cndmask_b32_e64 v29, 0, 1, vcc
	v_cmp_eq_u32_e32 vcc, 3, v28
	s_nop 1
	v_cndmask_b32_e64 v28, 0, 1, vcc
	v_or_b32_e32 v28, v28, v29
	v_add_u32_e32 v26, v26, v28
	v_cmp_gt_i32_e32 vcc, 31, v27
	s_nop 1
	v_cndmask_b32_e32 v26, v22, v26, vcc
	v_cmp_ne_u32_e32 vcc, 0, v24
	s_nop 1
	v_cndmask_b32_e32 v24, v22, v23, vcc
	v_cmp_eq_u32_e32 vcc, s93, v27
	s_nop 1
	v_cndmask_b32_e32 v24, v26, v24, vcc
	v_and_or_b32 v24, v25, s70, v24
	v_perm_b32 v7, v24, v7, s71
	global_store_dword v[16:17], v7, off offset:3072
	v_cvt_f64_f32_e32 v[24:25], v133
	v_cvt_f64_f32_e32 v[26:27], v149
	v_mul_f64 v[28:29], v[18:19], v[26:27]
	v_fma_f64 v[28:29], v[12:13], v[24:25], -v[28:29]
	v_mul_f64 v[26:27], v[12:13], v[26:27]
	v_fmac_f64_e32 v[26:27], v[18:19], v[24:25]
	v_ldexp_f64 v[24:25], v[28:29], 10
	v_and_or_b32 v7, v25, s33, v24
	v_cmp_ne_u32_e32 vcc, 0, v7
	v_lshrrev_b32_e32 v24, 8, v25
	v_bfe_u32 v28, v25, 20, 11
	v_cndmask_b32_e64 v7, 0, 1, vcc
	v_and_or_b32 v7, v24, s92, v7
	v_sub_u32_e32 v29, 0x3f1, v28
	v_or_b32_e32 v24, 0x1000, v7
	v_med3_i32 v29, v29, 0, 13
	v_lshrrev_b32_e32 v30, v29, v24
	v_lshlrev_b32_e32 v29, v29, v30
	v_cmp_ne_u32_e32 vcc, v29, v24
	v_add_u32_e32 v28, 0xfffffc10, v28
	v_lshl_or_b32 v29, v28, 12, v7
	v_cndmask_b32_e64 v24, 0, 1, vcc
	v_or_b32_e32 v24, v30, v24
	v_cmp_gt_i32_e32 vcc, 1, v28
	s_nop 1
	v_cndmask_b32_e32 v24, v29, v24, vcc
	v_and_b32_e32 v29, 7, v24
	v_cmp_lt_i32_e32 vcc, 5, v29
	v_lshrrev_b32_e32 v24, 2, v24
	s_nop 0
	v_cndmask_b32_e64 v30, 0, 1, vcc
	v_cmp_eq_u32_e32 vcc, 3, v29
	s_nop 1
	v_cndmask_b32_e64 v29, 0, 1, vcc
	v_or_b32_e32 v29, v29, v30
	v_add_u32_e32 v24, v24, v29
	v_cmp_gt_i32_e32 vcc, 31, v28
	s_nop 1
	v_cndmask_b32_e32 v24, v22, v24, vcc
	v_cmp_ne_u32_e32 vcc, 0, v7
	s_nop 1
	v_cndmask_b32_e32 v7, v22, v23, vcc
	v_cmp_eq_u32_e32 vcc, s93, v28
	s_nop 1
	v_cndmask_b32_e32 v7, v24, v7, vcc
	v_lshrrev_b32_e32 v24, 16, v25
	v_and_or_b32 v7, v24, s70, v7
	v_ldexp_f64 v[24:25], -v[26:27], 10
	v_and_or_b32 v24, v25, s33, v24
	v_cmp_ne_u32_e32 vcc, 0, v24
	v_lshrrev_b32_e32 v26, 8, v25
	v_bfe_u32 v27, v25, 20, 11
	v_cndmask_b32_e64 v24, 0, 1, vcc
	v_and_or_b32 v24, v26, s92, v24
	v_sub_u32_e32 v28, 0x3f1, v27
	v_or_b32_e32 v26, 0x1000, v24
	v_med3_i32 v28, v28, 0, 13
	v_lshrrev_b32_e32 v29, v28, v26
	v_lshlrev_b32_e32 v28, v28, v29
	v_cmp_ne_u32_e32 vcc, v28, v26
	v_add_u32_e32 v27, 0xfffffc10, v27
	v_lshl_or_b32 v28, v27, 12, v24
	v_cndmask_b32_e64 v26, 0, 1, vcc
	v_or_b32_e32 v26, v29, v26
	v_cmp_gt_i32_e32 vcc, 1, v27
	v_lshrrev_b32_e32 v25, 16, v25
	s_nop 0
	v_cndmask_b32_e32 v26, v28, v26, vcc
	v_and_b32_e32 v28, 7, v26
	v_cmp_lt_i32_e32 vcc, 5, v28
	v_lshrrev_b32_e32 v26, 2, v26
	s_nop 0
	v_cndmask_b32_e64 v29, 0, 1, vcc
	v_cmp_eq_u32_e32 vcc, 3, v28
	s_nop 1
	v_cndmask_b32_e64 v28, 0, 1, vcc
	v_or_b32_e32 v28, v28, v29
	v_add_u32_e32 v26, v26, v28
	v_cmp_gt_i32_e32 vcc, 31, v27
	s_nop 1
	v_cndmask_b32_e32 v26, v22, v26, vcc
	v_cmp_ne_u32_e32 vcc, 0, v24
	s_nop 1
	v_cndmask_b32_e32 v24, v22, v23, vcc
	v_cmp_eq_u32_e32 vcc, s93, v27
	s_nop 1
	v_cndmask_b32_e32 v24, v26, v24, vcc
	v_and_or_b32 v24, v25, s70, v24
	v_perm_b32 v7, v24, v7, s71
	global_store_dword v[16:17], v7, off offset:3328
	v_cvt_f64_f32_e32 v[24:25], v134
	v_cvt_f64_f32_e32 v[26:27], v150
	v_mul_f64 v[28:29], v[18:19], v[26:27]
	v_fma_f64 v[28:29], v[12:13], v[24:25], -v[28:29]
	v_mul_f64 v[26:27], v[12:13], v[26:27]
	v_fmac_f64_e32 v[26:27], v[18:19], v[24:25]
	v_ldexp_f64 v[24:25], v[28:29], 10
	v_and_or_b32 v7, v25, s33, v24
	v_cmp_ne_u32_e32 vcc, 0, v7
	v_lshrrev_b32_e32 v24, 8, v25
	v_bfe_u32 v28, v25, 20, 11
	v_cndmask_b32_e64 v7, 0, 1, vcc
	v_and_or_b32 v7, v24, s92, v7
	v_sub_u32_e32 v29, 0x3f1, v28
	v_or_b32_e32 v24, 0x1000, v7
	v_med3_i32 v29, v29, 0, 13
	v_lshrrev_b32_e32 v30, v29, v24
	v_lshlrev_b32_e32 v29, v29, v30
	v_cmp_ne_u32_e32 vcc, v29, v24
	v_add_u32_e32 v28, 0xfffffc10, v28
	v_lshl_or_b32 v29, v28, 12, v7
	v_cndmask_b32_e64 v24, 0, 1, vcc
	v_or_b32_e32 v24, v30, v24
	v_cmp_gt_i32_e32 vcc, 1, v28
	s_nop 1
	v_cndmask_b32_e32 v24, v29, v24, vcc
	v_and_b32_e32 v29, 7, v24
	v_cmp_lt_i32_e32 vcc, 5, v29
	v_lshrrev_b32_e32 v24, 2, v24
	s_nop 0
	v_cndmask_b32_e64 v30, 0, 1, vcc
	v_cmp_eq_u32_e32 vcc, 3, v29
	s_nop 1
	v_cndmask_b32_e64 v29, 0, 1, vcc
	v_or_b32_e32 v29, v29, v30
	v_add_u32_e32 v24, v24, v29
	v_cmp_gt_i32_e32 vcc, 31, v28
	s_nop 1
	v_cndmask_b32_e32 v24, v22, v24, vcc
	v_cmp_ne_u32_e32 vcc, 0, v7
	s_nop 1
	v_cndmask_b32_e32 v7, v22, v23, vcc
	v_cmp_eq_u32_e32 vcc, s93, v28
	s_nop 1
	v_cndmask_b32_e32 v7, v24, v7, vcc
	v_lshrrev_b32_e32 v24, 16, v25
	v_and_or_b32 v7, v24, s70, v7
	v_ldexp_f64 v[24:25], -v[26:27], 10
	v_and_or_b32 v24, v25, s33, v24
	v_cmp_ne_u32_e32 vcc, 0, v24
	v_lshrrev_b32_e32 v26, 8, v25
	v_bfe_u32 v27, v25, 20, 11
	v_cndmask_b32_e64 v24, 0, 1, vcc
	v_and_or_b32 v24, v26, s92, v24
	v_sub_u32_e32 v28, 0x3f1, v27
	v_or_b32_e32 v26, 0x1000, v24
	v_med3_i32 v28, v28, 0, 13
	v_lshrrev_b32_e32 v29, v28, v26
	v_lshlrev_b32_e32 v28, v28, v29
	v_cmp_ne_u32_e32 vcc, v28, v26
	v_add_u32_e32 v27, 0xfffffc10, v27
	v_lshl_or_b32 v28, v27, 12, v24
	v_cndmask_b32_e64 v26, 0, 1, vcc
	v_or_b32_e32 v26, v29, v26
	v_cmp_gt_i32_e32 vcc, 1, v27
	v_lshrrev_b32_e32 v25, 16, v25
	s_nop 0
	v_cndmask_b32_e32 v26, v28, v26, vcc
	v_and_b32_e32 v28, 7, v26
	v_cmp_lt_i32_e32 vcc, 5, v28
	v_lshrrev_b32_e32 v26, 2, v26
	s_nop 0
	v_cndmask_b32_e64 v29, 0, 1, vcc
	v_cmp_eq_u32_e32 vcc, 3, v28
	s_nop 1
	v_cndmask_b32_e64 v28, 0, 1, vcc
	v_or_b32_e32 v28, v28, v29
	v_add_u32_e32 v26, v26, v28
	v_cmp_gt_i32_e32 vcc, 31, v27
	s_nop 1
	v_cndmask_b32_e32 v26, v22, v26, vcc
	v_cmp_ne_u32_e32 vcc, 0, v24
	s_nop 1
	v_cndmask_b32_e32 v24, v22, v23, vcc
	v_cmp_eq_u32_e32 vcc, s93, v27
	s_nop 1
	v_cndmask_b32_e32 v24, v26, v24, vcc
	v_and_or_b32 v24, v25, s70, v24
	v_perm_b32 v7, v24, v7, s71
	global_store_dword v[16:17], v7, off offset:3584
	v_cvt_f64_f32_e32 v[14:15], v135
	v_cvt_f64_f32_e32 v[20:21], v151
	v_mul_f64 v[24:25], v[18:19], v[20:21]
	v_fma_f64 v[24:25], v[12:13], v[14:15], -v[24:25]
	v_mul_f64 v[12:13], v[12:13], v[20:21]
	v_fmac_f64_e32 v[12:13], v[18:19], v[14:15]
	v_ldexp_f64 v[14:15], v[24:25], 10
	v_and_or_b32 v7, v15, s33, v14
	v_cmp_ne_u32_e32 vcc, 0, v7
	v_lshrrev_b32_e32 v14, 8, v15
	v_bfe_u32 v18, v15, 20, 11
	v_cndmask_b32_e64 v7, 0, 1, vcc
	v_and_or_b32 v7, v14, s92, v7
	v_sub_u32_e32 v19, 0x3f1, v18
	v_or_b32_e32 v14, 0x1000, v7
	v_med3_i32 v19, v19, 0, 13
	v_lshrrev_b32_e32 v20, v19, v14
	v_lshlrev_b32_e32 v19, v19, v20
	v_cmp_ne_u32_e32 vcc, v19, v14
	v_add_u32_e32 v18, 0xfffffc10, v18
	v_lshl_or_b32 v19, v18, 12, v7
	v_cndmask_b32_e64 v14, 0, 1, vcc
	v_or_b32_e32 v14, v20, v14
	v_cmp_gt_i32_e32 vcc, 1, v18
	v_ldexp_f64 v[12:13], -v[12:13], 10
	v_and_or_b32 v12, v13, s33, v12
	v_cndmask_b32_e32 v14, v19, v14, vcc
	v_and_b32_e32 v19, 7, v14
	v_cmp_lt_i32_e32 vcc, 5, v19
	v_lshrrev_b32_e32 v14, 2, v14
	s_nop 0
	v_cndmask_b32_e64 v20, 0, 1, vcc
	v_cmp_eq_u32_e32 vcc, 3, v19
	s_nop 1
	v_cndmask_b32_e64 v19, 0, 1, vcc
	v_or_b32_e32 v19, v19, v20
	v_add_u32_e32 v14, v14, v19
	v_cmp_gt_i32_e32 vcc, 31, v18
	s_nop 1
	v_cndmask_b32_e32 v14, v22, v14, vcc
	v_cmp_ne_u32_e32 vcc, 0, v7
	s_nop 1
	v_cndmask_b32_e32 v7, v22, v23, vcc
	v_cmp_eq_u32_e32 vcc, s93, v18
	s_nop 1
	v_cndmask_b32_e32 v7, v14, v7, vcc
	v_lshrrev_b32_e32 v14, 16, v15
	v_cmp_ne_u32_e32 vcc, 0, v12
	v_and_or_b32 v7, v14, s70, v7
	v_lshrrev_b32_e32 v14, 8, v13
	v_cndmask_b32_e64 v12, 0, 1, vcc
	v_bfe_u32 v15, v13, 20, 11
	v_and_or_b32 v12, v14, s92, v12
	v_sub_u32_e32 v18, 0x3f1, v15
	v_or_b32_e32 v14, 0x1000, v12
	v_med3_i32 v18, v18, 0, 13
	v_lshrrev_b32_e32 v19, v18, v14
	v_lshlrev_b32_e32 v18, v18, v19
	v_cmp_ne_u32_e32 vcc, v18, v14
	v_add_u32_e32 v15, 0xfffffc10, v15
	v_lshl_or_b32 v18, v15, 12, v12
	v_cndmask_b32_e64 v14, 0, 1, vcc
	v_or_b32_e32 v14, v19, v14
	v_cmp_gt_i32_e32 vcc, 1, v15
	v_lshrrev_b32_e32 v13, 16, v13
	s_nop 0
	v_cndmask_b32_e32 v14, v18, v14, vcc
	v_and_b32_e32 v18, 7, v14
	v_cmp_lt_i32_e32 vcc, 5, v18
	v_lshrrev_b32_e32 v14, 2, v14
	s_nop 0
	v_cndmask_b32_e64 v19, 0, 1, vcc
	v_cmp_eq_u32_e32 vcc, 3, v18
	s_nop 1
	v_cndmask_b32_e64 v18, 0, 1, vcc
	v_or_b32_e32 v18, v18, v19
	v_add_u32_e32 v14, v14, v18
	v_cmp_gt_i32_e32 vcc, 31, v15
	s_nop 1
	v_cndmask_b32_e32 v14, v22, v14, vcc
	v_cmp_ne_u32_e32 vcc, 0, v12
	s_nop 1
	v_cndmask_b32_e32 v12, v22, v23, vcc
	v_cmp_eq_u32_e32 vcc, s93, v15
	s_nop 1
	v_cndmask_b32_e32 v12, v14, v12, vcc
	v_and_or_b32 v12, v13, s70, v12
	v_cmp_lt_i32_e32 vcc, s96, v0
	v_perm_b32 v7, v12, v7, s71
	s_or_b64 s[48:49], vcc, s[48:49]
	global_store_dword v[16:17], v7, off offset:3840
	s_andn2_b64 exec, exec, s[48:49]
	s_cbranch_execnz .LBB0_48
